# loader wave keeps priority 1 while it issues its ds_reads and LDS-DMA loads (s_setprio 0 moved from the segment start to just before its waits)
# speedup vs baseline: 1.0090x; 1.0001x over previous
; #define PG8_STAGE(bufoff, gbase, voff) do { _Pragma("unroll") for (int _i = 0; _i < 2; ++_i) \
;         __builtin_amdgcn_global_load_lds((const unsigned*)((const char*)(gbase) + (voff)[_i]), (PG8_LAS unsigned*)(lds + (bufoff) + ldsw + _i * 8192), 16, 0, 0); } while (0)
; #define PG8_LDA(dst, b, h) do { _Pragma("unroll") for (int m = 0; m < 4; ++m) _Pragma("unroll") for (int k = 0; k < 2; ++k) dst[m][k] = *(const PG8_LAS bf16x8*)(lds + PG8_SA(b, h) + aoff + m * 2048 + k * 1024); } while (0)
; #define PG8_LDB(dst, b, h) do { _Pragma("unroll") for (int n = 0; n < 2; ++n) _Pragma("unroll") for (int k = 0; k < 2; ++k) dst[n][k] = *(const PG8_LAS bf16x8*)(lds + PG8_SB(b, h) + boff + n * 2048 + k * 1024); } while (0)
; #define PG8_MMA(ai, bj, At, Bt) do { __builtin_amdgcn_s_setprio(1); _Pragma("unroll") for (int m = 0; m < 4; ++m) _Pragma("unroll") for (int n = 0; n < 2; ++n) _Pragma("unroll") for (int k = 0; k < 2; ++k) \
;         acc[ai][bj][m][n] = __builtin_amdgcn_mfma_f32_16x16x32_bf16(Bt[n][k], At[m][k], acc[ai][bj][m][n], 0, 0, 0); __builtin_amdgcn_s_setprio(0); } while (0)
; #define PG8_WAIT_V(n) asm volatile("s_waitcnt vmcnt(" #n ")" ::: "memory")
; #define PG8_WAIT_L(n) asm volatile("s_waitcnt lgkmcnt(" #n ")" ::: "memory")
; #define PG8_BAR __builtin_amdgcn_s_barrier()
; #define PG8_SCHED __builtin_amdgcn_sched_barrier(0)
; template <class Epi, class Sched, bool ALIGN_EPI = false, bool SP2 = false>
; __device__ __forceinline__ void gemm_phase(PG8_LAS unsigned char* lds, const Gemm g, const Sched& S, const Epi& E) {
;     ...
;             PG8_LDB(B0, 0, 0); PG8_LDB(B1, 0, 1); PG8_SCHED; PG8_LDA(At, 0, 0); PG8_STAGE(PG8_SA(1, 1), a1 + hstep, voffA);
;             PG8_WAIT_V(8); PG8_WAIT_L(0); PG8_BAR; PG8_MMA(0, 0, At, B0); PG8_MMA(0, 1, At, B1); PG8_BAR; PG8_SCHED;
;             PG8_LDA(At, 0, 1); PG8_STAGE(PG8_SB(0, 0), b2, voffB); PG8_STAGE(PG8_SB(0, 1), b2 + hstep, voffB); PG8_STAGE(PG8_SA(0, 0), a2, voffA);
;             PG8_WAIT_V(8); PG8_WAIT_L(0); PG8_BAR; PG8_MMA(1, 0, At, B0); PG8_MMA(1, 1, At, B1); PG8_BAR; PG8_SCHED;
.LBB0_1167:
	s_add_u32 s26, s36, 0xfff80080
	s_addc_u32 s38, s37, -1
	s_add_i32 s63, 0, 0x10000
	s_cmp_eq_u32 s62, 28
	s_cselect_b32 s43, s17, s38
	s_cselect_b32 s42, s30, s26
	v_add_u32_e32 v144, s63, v145
	s_cselect_b32 s39, s15, s57
	s_cselect_b32 s38, s55, s56
	s_add_i32 s26, 0, 0x14000
	ds_read_b128 v[154:157], v144
	ds_read_b128 v[158:161], v144 offset:1024
	ds_read_b128 v[162:165], v144 offset:2048
	ds_read_b128 v[166:169], v144 offset:3072
	v_add_u32_e32 v144, s26, v145
	ds_read_b128 v[170:173], v144
	ds_read_b128 v[174:177], v144 offset:1024
	ds_read_b128 v[182:185], v144 offset:2048
	ds_read_b128 v[186:189], v144 offset:3072
	v_lshl_add_u64 v[146:147], s[36:37], 0, v[140:141]
	s_add_i32 m0, s45, 0xc000
	ds_read_b128 v[190:193], v153
	ds_read_b128 v[194:197], v153 offset:1024
	ds_read_b128 v[198:201], v153 offset:2048
	ds_read_b128 v[202:205], v153 offset:3072
	ds_read_b128 v[206:209], v153 offset:4096
	ds_read_b128 v[210:213], v153 offset:5120
	ds_read_b128 v[214:217], v153 offset:6144
	ds_read_b128 v[218:221], v153 offset:7168
	global_load_lds_dwordx4 v[146:147], off
	v_lshl_add_u64 v[146:147], s[36:37], 0, v[142:143]
	s_add_i32 m0, s45, 0xe000
	s_nop 0
	global_load_lds_dwordx4 v[146:147], off
	s_setprio 0
	s_waitcnt vmcnt(8)
	s_waitcnt lgkmcnt(0)
	s_setprio 1
	s_barrier
	v_mfma_f32_16x16x32_bf16 v[80:83], v[154:157], v[190:193], v[80:83]
	v_mfma_f32_16x16x32_bf16 v[76:79], v[162:165], v[190:193], v[76:79]
	v_mfma_f32_16x16x32_bf16 v[64:67], v[154:157], v[198:201], v[64:67]
	v_mfma_f32_16x16x32_bf16 v[60:63], v[162:165], v[198:201], v[60:63]
	v_mfma_f32_16x16x32_bf16 v[56:59], v[154:157], v[206:209], v[56:59]
	v_mfma_f32_16x16x32_bf16 v[52:55], v[162:165], v[206:209], v[52:55]
	v_mfma_f32_16x16x32_bf16 v[44:47], v[154:157], v[214:217], v[44:47]
	v_mfma_f32_16x16x32_bf16 v[36:39], v[162:165], v[214:217], v[36:39]
	v_mfma_f32_16x16x32_bf16 v[80:83], v[158:161], v[194:197], v[80:83]
	v_mfma_f32_16x16x32_bf16 v[76:79], v[166:169], v[194:197], v[76:79]
	v_mfma_f32_16x16x32_bf16 v[64:67], v[158:161], v[202:205], v[64:67]
	v_mfma_f32_16x16x32_bf16 v[60:63], v[166:169], v[202:205], v[60:63]
	v_mfma_f32_16x16x32_bf16 v[56:59], v[158:161], v[210:213], v[56:59]
	v_mfma_f32_16x16x32_bf16 v[52:55], v[166:169], v[210:213], v[52:55]
	v_mfma_f32_16x16x32_bf16 v[44:47], v[158:161], v[218:221], v[44:47]
	v_mfma_f32_16x16x32_bf16 v[36:39], v[166:169], v[218:221], v[36:39]
	s_setprio 0
	s_setprio 1
	v_mfma_f32_16x16x32_bf16 v[128:131], v[170:173], v[190:193], v[128:131]
	v_mfma_f32_16x16x32_bf16 v[124:127], v[182:185], v[190:193], v[124:127]
	v_mfma_f32_16x16x32_bf16 v[120:123], v[170:173], v[198:201], v[120:123]
	v_mfma_f32_16x16x32_bf16 v[116:119], v[182:185], v[198:201], v[116:119]
	v_mfma_f32_16x16x32_bf16 v[112:115], v[170:173], v[206:209], v[112:115]
	v_mfma_f32_16x16x32_bf16 v[108:111], v[182:185], v[206:209], v[108:111]
	v_mfma_f32_16x16x32_bf16 v[104:107], v[170:173], v[214:217], v[104:107]
	v_mfma_f32_16x16x32_bf16 v[100:103], v[182:185], v[214:217], v[100:103]
	v_mfma_f32_16x16x32_bf16 v[128:131], v[174:177], v[194:197], v[128:131]
	v_mfma_f32_16x16x32_bf16 v[124:127], v[186:189], v[194:197], v[124:127]
	v_mfma_f32_16x16x32_bf16 v[120:123], v[174:177], v[202:205], v[120:123]
	v_mfma_f32_16x16x32_bf16 v[116:119], v[186:189], v[202:205], v[116:119]
	v_mfma_f32_16x16x32_bf16 v[112:115], v[174:177], v[210:213], v[112:115]
	v_mfma_f32_16x16x32_bf16 v[108:111], v[186:189], v[210:213], v[108:111]
	v_mfma_f32_16x16x32_bf16 v[104:107], v[174:177], v[218:221], v[104:107]
	v_mfma_f32_16x16x32_bf16 v[100:103], v[186:189], v[218:221], v[100:103]
	s_barrier
	s_add_i32 s63, s63, s44
	v_lshl_add_u64 v[146:147], s[38:39], 0, v[2:3]
	s_mov_b32 m0, s63
	ds_read_b128 v[190:193], v153 offset:16384
	ds_read_b128 v[194:197], v153 offset:17408
	ds_read_b128 v[198:201], v153 offset:18432
	ds_read_b128 v[202:205], v153 offset:19456
	ds_read_b128 v[206:209], v153 offset:20480
	ds_read_b128 v[210:213], v153 offset:21504
	ds_read_b128 v[214:217], v153 offset:22528
	ds_read_b128 v[218:221], v153 offset:23552
	global_load_lds_dwordx4 v[146:147], off
	s_add_i32 m0, s63, 0x2000
	s_add_u32 s66, s38, 0x80000
	v_lshl_add_u64 v[150:151], s[38:39], 0, v[132:133]
	s_addc_u32 s67, s39, 0
	s_add_i32 s26, s26, s44
	global_load_lds_dwordx4 v[150:151], off
	v_lshl_add_u64 v[178:179], s[66:67], 0, v[2:3]
	s_mov_b32 m0, s26
	v_lshl_add_u64 v[222:223], s[42:43], 0, v[134:135]
	global_load_lds_dwordx4 v[178:179], off
	v_lshl_add_u64 v[178:179], s[66:67], 0, v[132:133]
	s_add_i32 m0, s26, 0x2000
	s_nop 0
	global_load_lds_dwordx4 v[178:179], off
	v_lshl_add_u64 v[178:179], s[42:43], 0, v[136:137]
	s_mov_b32 m0, s45
	s_nop 0
	global_load_lds_dwordx4 v[178:179], off
	s_mov_b32 m0, s46
	s_nop 0
	global_load_lds_dwordx4 v[222:223], off
	s_setprio 0
	s_waitcnt vmcnt(8)
	s_waitcnt lgkmcnt(0)
	s_setprio 1
	s_barrier
; #define PG8_STAGE(bufoff, gbase, voff) do { _Pragma("unroll") for (int _i = 0; _i < 2; ++_i) \
;         __builtin_amdgcn_global_load_lds((const unsigned*)((const char*)(gbase) + (voff)[_i]), (PG8_LAS unsigned*)(lds + (bufoff) + ldsw + _i * 8192), 16, 0, 0); } while (0)
; #define PG8_LDA(dst, b, h) do { _Pragma("unroll") for (int m = 0; m < 4; ++m) _Pragma("unroll") for (int k = 0; k < 2; ++k) dst[m][k] = *(const PG8_LAS bf16x8*)(lds + PG8_SA(b, h) + aoff + m * 2048 + k * 1024); } while (0)
; #define PG8_LDB(dst, b, h) do { _Pragma("unroll") for (int n = 0; n < 2; ++n) _Pragma("unroll") for (int k = 0; k < 2; ++k) dst[n][k] = *(const PG8_LAS bf16x8*)(lds + PG8_SB(b, h) + boff + n * 2048 + k * 1024); } while (0)
; #define PG8_MMA(ai, bj, At, Bt) do { __builtin_amdgcn_s_setprio(1); _Pragma("unroll") for (int m = 0; m < 4; ++m) _Pragma("unroll") for (int n = 0; n < 2; ++n) _Pragma("unroll") for (int k = 0; k < 2; ++k) \
;         acc[ai][bj][m][n] = __builtin_amdgcn_mfma_f32_16x16x32_bf16(Bt[n][k], At[m][k], acc[ai][bj][m][n], 0, 0, 0); __builtin_amdgcn_s_setprio(0); } while (0)
; #define PG8_WAIT_V(n) asm volatile("s_waitcnt vmcnt(" #n ")" ::: "memory")
; #define PG8_WAIT_L(n) asm volatile("s_waitcnt lgkmcnt(" #n ")" ::: "memory")
; #define PG8_BAR __builtin_amdgcn_s_barrier()
; #define PG8_SCHED __builtin_amdgcn_sched_barrier(0)
; template <class Epi, class Sched, bool ALIGN_EPI = false, bool SP2 = false>
; __device__ __forceinline__ void gemm_phase(PG8_LAS unsigned char* lds, const Gemm g, const Sched& S, const Epi& E) {
;     ...
;             PG8_WAIT_V(8); PG8_WAIT_L(0); PG8_BAR; PG8_MMA(1, 0, At, B0); PG8_MMA(1, 1, At, B1); PG8_BAR; PG8_SCHED;
;             PG8_LDB(B0, 1, 0); PG8_LDB(B1, 1, 1); PG8_SCHED; PG8_LDA(At, 1, 0); PG8_STAGE(PG8_SA(0, 1), a2 + hstep, voffA);
;             PG8_WAIT_V(8); PG8_WAIT_L(0); PG8_BAR; PG8_MMA(0, 0, At, B0); PG8_MMA(0, 1, At, B1); PG8_BAR; PG8_SCHED;
	v_mfma_f32_16x16x32_bf16 v[32:35], v[154:157], v[190:193], v[32:35]
	v_mfma_f32_16x16x32_bf16 v[28:31], v[162:165], v[190:193], v[28:31]
	v_mfma_f32_16x16x32_bf16 v[24:27], v[154:157], v[198:201], v[24:27]
	v_mfma_f32_16x16x32_bf16 v[20:23], v[162:165], v[198:201], v[20:23]
	v_mfma_f32_16x16x32_bf16 v[16:19], v[154:157], v[206:209], v[16:19]
	v_mfma_f32_16x16x32_bf16 v[12:15], v[162:165], v[206:209], v[12:15]
	v_mfma_f32_16x16x32_bf16 v[8:11], v[154:157], v[214:217], v[8:11]
	v_mfma_f32_16x16x32_bf16 v[4:7], v[162:165], v[214:217], v[4:7]
	v_mfma_f32_16x16x32_bf16 v[32:35], v[158:161], v[194:197], v[32:35]
	v_mfma_f32_16x16x32_bf16 v[28:31], v[166:169], v[194:197], v[28:31]
	v_mfma_f32_16x16x32_bf16 v[24:27], v[158:161], v[202:205], v[24:27]
	v_mfma_f32_16x16x32_bf16 v[20:23], v[166:169], v[202:205], v[20:23]
	v_mfma_f32_16x16x32_bf16 v[16:19], v[158:161], v[210:213], v[16:19]
	v_mfma_f32_16x16x32_bf16 v[12:15], v[166:169], v[210:213], v[12:15]
	v_mfma_f32_16x16x32_bf16 v[8:11], v[158:161], v[218:221], v[8:11]
	v_mfma_f32_16x16x32_bf16 v[4:7], v[166:169], v[218:221], v[4:7]
	s_setprio 0
	s_setprio 1
	v_mfma_f32_16x16x32_bf16 v[96:99], v[170:173], v[190:193], v[96:99]
	v_mfma_f32_16x16x32_bf16 v[92:95], v[182:185], v[190:193], v[92:95]
	v_mfma_f32_16x16x32_bf16 v[88:91], v[170:173], v[198:201], v[88:91]
	v_mfma_f32_16x16x32_bf16 v[84:87], v[182:185], v[198:201], v[84:87]
	v_mfma_f32_16x16x32_bf16 v[72:75], v[170:173], v[206:209], v[72:75]
	v_mfma_f32_16x16x32_bf16 v[68:71], v[182:185], v[206:209], v[68:71]
	v_mfma_f32_16x16x32_bf16 v[48:51], v[170:173], v[214:217], v[48:51]
	v_mfma_f32_16x16x32_bf16 v[40:43], v[182:185], v[214:217], v[40:43]
	v_mfma_f32_16x16x32_bf16 v[96:99], v[174:177], v[194:197], v[96:99]
	v_mfma_f32_16x16x32_bf16 v[92:95], v[186:189], v[194:197], v[92:95]
	v_mfma_f32_16x16x32_bf16 v[88:91], v[174:177], v[202:205], v[88:91]
	v_mfma_f32_16x16x32_bf16 v[84:87], v[186:189], v[202:205], v[84:87]
	v_mfma_f32_16x16x32_bf16 v[72:75], v[174:177], v[210:213], v[72:75]
	v_mfma_f32_16x16x32_bf16 v[68:71], v[186:189], v[210:213], v[68:71]
	v_mfma_f32_16x16x32_bf16 v[48:51], v[174:177], v[218:221], v[48:51]
	v_mfma_f32_16x16x32_bf16 v[40:43], v[186:189], v[218:221], v[40:43]
	s_barrier
	s_add_i32 s26, 0, 0x18000
	v_add_u32_e32 v144, s26, v145
	s_add_i32 s63, 0, 0x1c000
	ds_read_b128 v[154:157], v144
	ds_read_b128 v[158:161], v144 offset:1024
	ds_read_b128 v[162:165], v144 offset:2048
	ds_read_b128 v[166:169], v144 offset:3072
	v_add_u32_e32 v144, s63, v145
	ds_read_b128 v[170:173], v144
	ds_read_b128 v[174:177], v144 offset:1024
	ds_read_b128 v[182:185], v144 offset:2048
	ds_read_b128 v[186:189], v144 offset:3072
	s_add_u32 s42, s42, 0x80000
	s_addc_u32 s43, s43, 0
	s_mov_b32 m0, s47
	v_lshl_add_u64 v[224:225], s[42:43], 0, v[136:137]
	ds_read_b128 v[190:193], v153 offset:32768
	ds_read_b128 v[194:197], v153 offset:33792
	ds_read_b128 v[198:201], v153 offset:34816
	ds_read_b128 v[202:205], v153 offset:35840
	ds_read_b128 v[206:209], v153 offset:36864
	ds_read_b128 v[210:213], v153 offset:37888
	ds_read_b128 v[214:217], v153 offset:38912
	ds_read_b128 v[218:221], v153 offset:39936
	global_load_lds_dwordx4 v[224:225], off
	v_lshl_add_u64 v[224:225], s[42:43], 0, v[134:135]
	s_mov_b32 m0, s50
	s_nop 0
	global_load_lds_dwordx4 v[224:225], off
	s_setprio 0
	s_waitcnt vmcnt(8)
	s_waitcnt lgkmcnt(0)
	s_setprio 1
	s_barrier
	v_mfma_f32_16x16x32_bf16 v[80:83], v[154:157], v[190:193], v[80:83]
	v_mfma_f32_16x16x32_bf16 v[76:79], v[162:165], v[190:193], v[76:79]
	v_mfma_f32_16x16x32_bf16 v[64:67], v[154:157], v[198:201], v[64:67]
	v_mfma_f32_16x16x32_bf16 v[60:63], v[162:165], v[198:201], v[60:63]
	v_mfma_f32_16x16x32_bf16 v[56:59], v[154:157], v[206:209], v[56:59]
	v_mfma_f32_16x16x32_bf16 v[52:55], v[162:165], v[206:209], v[52:55]
	v_mfma_f32_16x16x32_bf16 v[44:47], v[154:157], v[214:217], v[44:47]
	v_mfma_f32_16x16x32_bf16 v[36:39], v[162:165], v[214:217], v[36:39]
	v_mfma_f32_16x16x32_bf16 v[80:83], v[158:161], v[194:197], v[80:83]
	v_mfma_f32_16x16x32_bf16 v[76:79], v[166:169], v[194:197], v[76:79]
	v_mfma_f32_16x16x32_bf16 v[64:67], v[158:161], v[202:205], v[64:67]
	v_mfma_f32_16x16x32_bf16 v[60:63], v[166:169], v[202:205], v[60:63]
	v_mfma_f32_16x16x32_bf16 v[56:59], v[158:161], v[210:213], v[56:59]
	v_mfma_f32_16x16x32_bf16 v[52:55], v[166:169], v[210:213], v[52:55]
	v_mfma_f32_16x16x32_bf16 v[44:47], v[158:161], v[218:221], v[44:47]
	v_mfma_f32_16x16x32_bf16 v[36:39], v[166:169], v[218:221], v[36:39]
	s_setprio 0
	s_setprio 1
	v_mfma_f32_16x16x32_bf16 v[128:131], v[170:173], v[190:193], v[128:131]
	v_mfma_f32_16x16x32_bf16 v[124:127], v[182:185], v[190:193], v[124:127]
	v_mfma_f32_16x16x32_bf16 v[120:123], v[170:173], v[198:201], v[120:123]
	v_mfma_f32_16x16x32_bf16 v[116:119], v[182:185], v[198:201], v[116:119]
	v_mfma_f32_16x16x32_bf16 v[112:115], v[170:173], v[206:209], v[112:115]
	v_mfma_f32_16x16x32_bf16 v[108:111], v[182:185], v[206:209], v[108:111]
	v_mfma_f32_16x16x32_bf16 v[104:107], v[170:173], v[214:217], v[104:107]
	v_mfma_f32_16x16x32_bf16 v[100:103], v[182:185], v[214:217], v[100:103]
	v_mfma_f32_16x16x32_bf16 v[128:131], v[174:177], v[194:197], v[128:131]
	v_mfma_f32_16x16x32_bf16 v[124:127], v[186:189], v[194:197], v[124:127]
	v_mfma_f32_16x16x32_bf16 v[120:123], v[174:177], v[202:205], v[120:123]
	v_mfma_f32_16x16x32_bf16 v[116:119], v[186:189], v[202:205], v[116:119]
	v_mfma_f32_16x16x32_bf16 v[112:115], v[174:177], v[210:213], v[112:115]
	v_mfma_f32_16x16x32_bf16 v[108:111], v[186:189], v[210:213], v[108:111]
	v_mfma_f32_16x16x32_bf16 v[104:107], v[174:177], v[218:221], v[104:107]
	v_mfma_f32_16x16x32_bf16 v[100:103], v[186:189], v[218:221], v[100:103]
	s_barrier
; #define PG8_STAGE(bufoff, gbase, voff) do { _Pragma("unroll") for (int _i = 0; _i < 2; ++_i) \
;         __builtin_amdgcn_global_load_lds((const unsigned*)((const char*)(gbase) + (voff)[_i]), (PG8_LAS unsigned*)(lds + (bufoff) + ldsw + _i * 8192), 16, 0, 0); } while (0)
; #define PG8_LDA(dst, b, h) do { _Pragma("unroll") for (int m = 0; m < 4; ++m) _Pragma("unroll") for (int k = 0; k < 2; ++k) dst[m][k] = *(const PG8_LAS bf16x8*)(lds + PG8_SA(b, h) + aoff + m * 2048 + k * 1024); } while (0)
; #define PG8_MMA(ai, bj, At, Bt) do { __builtin_amdgcn_s_setprio(1); _Pragma("unroll") for (int m = 0; m < 4; ++m) _Pragma("unroll") for (int n = 0; n < 2; ++n) _Pragma("unroll") for (int k = 0; k < 2; ++k) \
;         acc[ai][bj][m][n] = __builtin_amdgcn_mfma_f32_16x16x32_bf16(Bt[n][k], At[m][k], acc[ai][bj][m][n], 0, 0, 0); __builtin_amdgcn_s_setprio(0); } while (0)
; #define PG8_WAIT_V(n) asm volatile("s_waitcnt vmcnt(" #n ")" ::: "memory")
; #define PG8_WAIT_L(n) asm volatile("s_waitcnt lgkmcnt(" #n ")" ::: "memory")
; #define PG8_BAR __builtin_amdgcn_s_barrier()
; #define PG8_SCHED __builtin_amdgcn_sched_barrier(0)
; template <class Epi, class Sched, bool ALIGN_EPI = false, bool SP2 = false>
; __device__ __forceinline__ void gemm_phase(PG8_LAS unsigned char* lds, const Gemm g, const Sched& S, const Epi& E) {
;     ...
;         for (int t = 0; t < nt; t += 2) {
;             const bool last = (t == nt - 2);
;             const char* a1 = cA + (size_t)(t + 1) * kstep;
;             const char* a2 = last ? nA : cA + (size_t)(t + 2) * kstep; const char* b2 = last ? nB : cB + (size_t)(t + 2) * kstep;
;     ...
;             PG8_LDA(At, 1, 1); PG8_STAGE(PG8_SB(1, 0), b3, voffB); PG8_STAGE(PG8_SB(1, 1), b3 + hstep, voffB); PG8_STAGE(PG8_SA(1, 0), a3, voffA);
;             PG8_WAIT_V(8); PG8_WAIT_L(0); PG8_BAR; PG8_MMA(1, 0, At, B0); PG8_MMA(1, 1, At, B1); PG8_BAR; PG8_SCHED;
	s_add_i32 s26, s26, s44
	v_lshl_add_u64 v[146:147], v[146:147], 0, s[60:61]
	s_mov_b32 m0, s26
	ds_read_b128 v[190:193], v153 offset:49152
	ds_read_b128 v[194:197], v153 offset:50176
	ds_read_b128 v[198:201], v153 offset:51200
	ds_read_b128 v[202:205], v153 offset:52224
	ds_read_b128 v[206:209], v153 offset:53248
	ds_read_b128 v[210:213], v153 offset:54272
	ds_read_b128 v[214:217], v153 offset:55296
	ds_read_b128 v[218:221], v153 offset:56320
	global_load_lds_dwordx4 v[146:147], off
	s_add_i32 m0, s26, 0x2000
	s_add_u32 s38, s38, 0x80080
	v_lshl_add_u64 v[146:147], v[150:151], 0, s[60:61]
	s_addc_u32 s39, s39, 0
	s_add_i32 s26, s63, s44
	global_load_lds_dwordx4 v[146:147], off
	v_lshl_add_u64 v[146:147], s[38:39], 0, v[2:3]
	s_mov_b32 m0, s26
	s_nop 0
	global_load_lds_dwordx4 v[146:147], off
	v_lshl_add_u64 v[146:147], s[38:39], 0, v[132:133]
	s_add_i32 m0, s26, 0x2000
	s_nop 0
	global_load_lds_dwordx4 v[146:147], off
	v_lshl_add_u64 v[146:147], v[178:179], 0, s[60:61]
	s_mov_b32 m0, s51
	s_nop 0
	global_load_lds_dwordx4 v[146:147], off
	v_lshl_add_u64 v[146:147], v[222:223], 0, s[60:61]
	s_mov_b32 m0, s52
	s_nop 0
	global_load_lds_dwordx4 v[146:147], off
	s_setprio 0
	s_waitcnt vmcnt(8)
	s_waitcnt lgkmcnt(0)
	s_setprio 1
	s_barrier
	v_mfma_f32_16x16x32_bf16 v[32:35], v[154:157], v[190:193], v[32:35]
	v_mfma_f32_16x16x32_bf16 v[28:31], v[162:165], v[190:193], v[28:31]
	v_mfma_f32_16x16x32_bf16 v[24:27], v[154:157], v[198:201], v[24:27]
	v_mfma_f32_16x16x32_bf16 v[20:23], v[162:165], v[198:201], v[20:23]
	v_mfma_f32_16x16x32_bf16 v[16:19], v[154:157], v[206:209], v[16:19]
	v_mfma_f32_16x16x32_bf16 v[12:15], v[162:165], v[206:209], v[12:15]
	v_mfma_f32_16x16x32_bf16 v[8:11], v[154:157], v[214:217], v[8:11]
	v_mfma_f32_16x16x32_bf16 v[4:7], v[162:165], v[214:217], v[4:7]
	v_mfma_f32_16x16x32_bf16 v[32:35], v[158:161], v[194:197], v[32:35]
	v_mfma_f32_16x16x32_bf16 v[28:31], v[166:169], v[194:197], v[28:31]
	v_mfma_f32_16x16x32_bf16 v[24:27], v[158:161], v[202:205], v[24:27]
	v_mfma_f32_16x16x32_bf16 v[20:23], v[166:169], v[202:205], v[20:23]
	v_mfma_f32_16x16x32_bf16 v[16:19], v[158:161], v[210:213], v[16:19]
	v_mfma_f32_16x16x32_bf16 v[12:15], v[166:169], v[210:213], v[12:15]
	v_mfma_f32_16x16x32_bf16 v[8:11], v[158:161], v[218:221], v[8:11]
	v_mfma_f32_16x16x32_bf16 v[4:7], v[166:169], v[218:221], v[4:7]
	s_setprio 0
	s_setprio 1
	v_mfma_f32_16x16x32_bf16 v[96:99], v[170:173], v[190:193], v[96:99]
	v_mfma_f32_16x16x32_bf16 v[92:95], v[182:185], v[190:193], v[92:95]
	v_mfma_f32_16x16x32_bf16 v[88:91], v[170:173], v[198:201], v[88:91]
	v_mfma_f32_16x16x32_bf16 v[84:87], v[182:185], v[198:201], v[84:87]
	v_mfma_f32_16x16x32_bf16 v[72:75], v[170:173], v[206:209], v[72:75]
	v_mfma_f32_16x16x32_bf16 v[68:71], v[182:185], v[206:209], v[68:71]
	v_mfma_f32_16x16x32_bf16 v[48:51], v[170:173], v[214:217], v[48:51]
	v_mfma_f32_16x16x32_bf16 v[40:43], v[182:185], v[214:217], v[40:43]
	v_mfma_f32_16x16x32_bf16 v[96:99], v[174:177], v[194:197], v[96:99]
	v_mfma_f32_16x16x32_bf16 v[92:95], v[186:189], v[194:197], v[92:95]
	v_mfma_f32_16x16x32_bf16 v[88:91], v[174:177], v[202:205], v[88:91]
	v_mfma_f32_16x16x32_bf16 v[84:87], v[186:189], v[202:205], v[84:87]
	v_mfma_f32_16x16x32_bf16 v[72:75], v[174:177], v[210:213], v[72:75]
	v_mfma_f32_16x16x32_bf16 v[68:71], v[186:189], v[210:213], v[68:71]
	v_mfma_f32_16x16x32_bf16 v[48:51], v[174:177], v[218:221], v[48:51]
	v_mfma_f32_16x16x32_bf16 v[40:43], v[186:189], v[218:221], v[40:43]
	s_barrier
	s_add_i32 s62, s62, 2
	s_add_u32 s36, s36, 0x100
	s_addc_u32 s37, s37, 0
	s_add_u32 s56, s56, 0x100
	s_addc_u32 s57, s57, 0
	s_cmp_gt_u32 s62, 29
	s_cbranch_scc0 .LBB0_1167
	s_and_b64 vcc, exec, s[10:11]
	s_cbranch_vccz .LBB0_1170
	s_barrier

; #define PG8_STAGE(bufoff, gbase, voff) do { _Pragma("unroll") for (int _i = 0; _i < 2; ++_i) \
;         __builtin_amdgcn_global_load_lds((const unsigned*)((const char*)(gbase) + (voff)[_i]), (PG8_LAS unsigned*)(lds + (bufoff) + ldsw + _i * 8192), 16, 0, 0); } while (0)
; #define PG8_LDA(dst, b, h) do { _Pragma("unroll") for (int m = 0; m < 4; ++m) _Pragma("unroll") for (int k = 0; k < 2; ++k) dst[m][k] = *(const PG8_LAS bf16x8*)(lds + PG8_SA(b, h) + aoff + m * 2048 + k * 1024); } while (0)
; #define PG8_LDB(dst, b, h) do { _Pragma("unroll") for (int n = 0; n < 2; ++n) _Pragma("unroll") for (int k = 0; k < 2; ++k) dst[n][k] = *(const PG8_LAS bf16x8*)(lds + PG8_SB(b, h) + boff + n * 2048 + k * 1024); } while (0)
; #define PG8_MMA(ai, bj, At, Bt) do { __builtin_amdgcn_s_setprio(1); _Pragma("unroll") for (int m = 0; m < 4; ++m) _Pragma("unroll") for (int n = 0; n < 2; ++n) _Pragma("unroll") for (int k = 0; k < 2; ++k) \
;         acc[ai][bj][m][n] = __builtin_amdgcn_mfma_f32_16x16x32_bf16(Bt[n][k], At[m][k], acc[ai][bj][m][n], 0, 0, 0); __builtin_amdgcn_s_setprio(0); } while (0)
; #define PG8_WAIT_V(n) asm volatile("s_waitcnt vmcnt(" #n ")" ::: "memory")
; #define PG8_WAIT_L(n) asm volatile("s_waitcnt lgkmcnt(" #n ")" ::: "memory")
; #define PG8_BAR __builtin_amdgcn_s_barrier()
; #define PG8_SCHED __builtin_amdgcn_sched_barrier(0)
; template <class Epi, class Sched, bool ALIGN_EPI = false, bool SP2 = false>
; __device__ __forceinline__ void gemm_phase(PG8_LAS unsigned char* lds, const Gemm g, const Sched& S, const Epi& E) {
;     ...
;             PG8_LDB(B0, 0, 0); PG8_LDB(B1, 0, 1); PG8_SCHED; PG8_LDA(At, 0, 0); PG8_STAGE(PG8_SA(1, 1), a1 + hstep, voffA);
;             PG8_WAIT_V(8); PG8_WAIT_L(0); PG8_BAR; PG8_MMA(0, 0, At, B0); PG8_MMA(0, 1, At, B1); PG8_BAR; PG8_SCHED;
;             PG8_LDA(At, 0, 1); PG8_STAGE(PG8_SB(0, 0), b2, voffB); PG8_STAGE(PG8_SB(0, 1), b2 + hstep, voffB); PG8_STAGE(PG8_SA(0, 0), a2, voffA);
;             PG8_WAIT_V(8); PG8_WAIT_L(0); PG8_BAR; PG8_MMA(1, 0, At, B0); PG8_MMA(1, 1, At, B1); PG8_BAR; PG8_SCHED;
.LBB0_1961:
	s_add_u32 s26, s38, 0xfff80080
	s_addc_u32 s31, s39, -1
	s_add_i32 s67, 0, 0x10000
	s_cmp_eq_u32 s66, 28
	s_cselect_b32 s45, s21, s31
	s_cselect_b32 s44, s57, s26
	s_cselect_b32 s43, s19, s64
	s_cselect_b32 s42, s62, s63
	s_add_i32 s26, 0, 0x14000
	v_add_u32_e32 v128, s67, v178
	v_add_u32_e32 v170, s26, v178
	ds_read_b128 v[116:119], v128
	ds_read_b128 v[120:123], v128 offset:1024
	ds_read_b128 v[124:127], v128 offset:2048
	ds_read_b128 v[128:131], v128 offset:3072
	ds_read_b128 v[132:135], v170
	ds_read_b128 v[136:139], v170 offset:1024
	ds_read_b128 v[166:169], v170 offset:2048
	ds_read_b128 v[170:173], v170 offset:3072
	v_lshl_add_u64 v[210:211], s[38:39], 0, v[162:163]
	s_add_i32 m0, s47, 0xc000
	ds_read_b128 v[174:177], v181
	ds_read_b128 v[182:185], v181 offset:1024
	ds_read_b128 v[186:189], v181 offset:2048
	ds_read_b128 v[190:193], v181 offset:3072
	ds_read_b128 v[194:197], v181 offset:4096
	ds_read_b128 v[198:201], v181 offset:5120
	ds_read_b128 v[202:205], v181 offset:6144
	ds_read_b128 v[206:209], v181 offset:7168
	global_load_lds_dwordx4 v[210:211], off
	v_lshl_add_u64 v[210:211], s[38:39], 0, v[164:165]
	s_add_i32 m0, s47, 0xe000
	s_nop 0
	global_load_lds_dwordx4 v[210:211], off
	s_setprio 0
	s_waitcnt vmcnt(8)
	s_waitcnt lgkmcnt(0)
	s_setprio 1
	s_barrier
	v_mfma_f32_16x16x32_bf16 v[152:155], v[116:119], v[174:177], v[152:155]
	v_mfma_f32_16x16x32_bf16 v[148:151], v[124:127], v[174:177], v[148:151]
	v_mfma_f32_16x16x32_bf16 v[112:115], v[116:119], v[186:189], v[112:115]
	v_mfma_f32_16x16x32_bf16 v[108:111], v[124:127], v[186:189], v[108:111]
	v_mfma_f32_16x16x32_bf16 v[96:99], v[116:119], v[194:197], v[96:99]
	v_mfma_f32_16x16x32_bf16 v[92:95], v[124:127], v[194:197], v[92:95]
	v_mfma_f32_16x16x32_bf16 v[80:83], v[116:119], v[202:205], v[80:83]
	v_mfma_f32_16x16x32_bf16 v[76:79], v[124:127], v[202:205], v[76:79]
	v_mfma_f32_16x16x32_bf16 v[152:155], v[120:123], v[182:185], v[152:155]
	v_mfma_f32_16x16x32_bf16 v[148:151], v[128:131], v[182:185], v[148:151]
	v_mfma_f32_16x16x32_bf16 v[112:115], v[120:123], v[190:193], v[112:115]
	v_mfma_f32_16x16x32_bf16 v[108:111], v[128:131], v[190:193], v[108:111]
	v_mfma_f32_16x16x32_bf16 v[96:99], v[120:123], v[198:201], v[96:99]
	v_mfma_f32_16x16x32_bf16 v[92:95], v[128:131], v[198:201], v[92:95]
	v_mfma_f32_16x16x32_bf16 v[80:83], v[120:123], v[206:209], v[80:83]
	v_mfma_f32_16x16x32_bf16 v[76:79], v[128:131], v[206:209], v[76:79]
	s_setprio 0
	s_setprio 1
	v_mfma_f32_16x16x32_bf16 v[144:147], v[132:135], v[174:177], v[144:147]
	v_mfma_f32_16x16x32_bf16 v[140:143], v[166:169], v[174:177], v[140:143]
	v_mfma_f32_16x16x32_bf16 v[104:107], v[132:135], v[186:189], v[104:107]
	v_mfma_f32_16x16x32_bf16 v[100:103], v[166:169], v[186:189], v[100:103]
	v_mfma_f32_16x16x32_bf16 v[88:91], v[132:135], v[194:197], v[88:91]
	v_mfma_f32_16x16x32_bf16 v[84:87], v[166:169], v[194:197], v[84:87]
	v_mfma_f32_16x16x32_bf16 v[72:75], v[132:135], v[202:205], v[72:75]
	v_mfma_f32_16x16x32_bf16 v[68:71], v[166:169], v[202:205], v[68:71]
	v_mfma_f32_16x16x32_bf16 v[144:147], v[136:139], v[182:185], v[144:147]
	v_mfma_f32_16x16x32_bf16 v[140:143], v[170:173], v[182:185], v[140:143]
	v_mfma_f32_16x16x32_bf16 v[104:107], v[136:139], v[190:193], v[104:107]
	v_mfma_f32_16x16x32_bf16 v[100:103], v[170:173], v[190:193], v[100:103]
	v_mfma_f32_16x16x32_bf16 v[88:91], v[136:139], v[198:201], v[88:91]
	v_mfma_f32_16x16x32_bf16 v[84:87], v[170:173], v[198:201], v[84:87]
	v_mfma_f32_16x16x32_bf16 v[72:75], v[136:139], v[206:209], v[72:75]
	v_mfma_f32_16x16x32_bf16 v[68:71], v[170:173], v[206:209], v[68:71]
	s_barrier
	s_add_i32 s31, s67, s46
	v_lshl_add_u64 v[210:211], s[42:43], 0, v[2:3]
	s_mov_b32 m0, s31
	ds_read_b128 v[174:177], v181 offset:16384
	ds_read_b128 v[182:185], v181 offset:17408
	ds_read_b128 v[186:189], v181 offset:18432
	ds_read_b128 v[190:193], v181 offset:19456
	ds_read_b128 v[194:197], v181 offset:20480
	ds_read_b128 v[198:201], v181 offset:21504
	ds_read_b128 v[202:205], v181 offset:22528
	ds_read_b128 v[206:209], v181 offset:23552
	global_load_lds_dwordx4 v[210:211], off
	s_add_i32 m0, s31, 0x2000
	s_add_u32 s68, s42, 0x80000
	v_lshl_add_u64 v[212:213], s[42:43], 0, v[156:157]
	s_addc_u32 s69, s43, 0
	s_add_i32 s26, s26, s46
	global_load_lds_dwordx4 v[212:213], off
	v_lshl_add_u64 v[214:215], s[68:69], 0, v[2:3]
	s_mov_b32 m0, s26
	v_lshl_add_u64 v[216:217], s[44:45], 0, v[158:159]
	global_load_lds_dwordx4 v[214:215], off
	v_lshl_add_u64 v[214:215], s[68:69], 0, v[156:157]
	s_add_i32 m0, s26, 0x2000
	s_nop 0
	global_load_lds_dwordx4 v[214:215], off
	v_lshl_add_u64 v[214:215], s[44:45], 0, v[160:161]
	s_mov_b32 m0, s47
	s_nop 0
	global_load_lds_dwordx4 v[214:215], off
	s_mov_b32 m0, s50
	s_nop 0
	global_load_lds_dwordx4 v[216:217], off
	s_setprio 0
	s_waitcnt vmcnt(8)
	s_waitcnt lgkmcnt(0)
	s_setprio 1
	s_barrier
; #define PG8_STAGE(bufoff, gbase, voff) do { _Pragma("unroll") for (int _i = 0; _i < 2; ++_i) \
;         __builtin_amdgcn_global_load_lds((const unsigned*)((const char*)(gbase) + (voff)[_i]), (PG8_LAS unsigned*)(lds + (bufoff) + ldsw + _i * 8192), 16, 0, 0); } while (0)
; #define PG8_LDA(dst, b, h) do { _Pragma("unroll") for (int m = 0; m < 4; ++m) _Pragma("unroll") for (int k = 0; k < 2; ++k) dst[m][k] = *(const PG8_LAS bf16x8*)(lds + PG8_SA(b, h) + aoff + m * 2048 + k * 1024); } while (0)
; #define PG8_LDB(dst, b, h) do { _Pragma("unroll") for (int n = 0; n < 2; ++n) _Pragma("unroll") for (int k = 0; k < 2; ++k) dst[n][k] = *(const PG8_LAS bf16x8*)(lds + PG8_SB(b, h) + boff + n * 2048 + k * 1024); } while (0)
; #define PG8_MMA(ai, bj, At, Bt) do { __builtin_amdgcn_s_setprio(1); _Pragma("unroll") for (int m = 0; m < 4; ++m) _Pragma("unroll") for (int n = 0; n < 2; ++n) _Pragma("unroll") for (int k = 0; k < 2; ++k) \
;         acc[ai][bj][m][n] = __builtin_amdgcn_mfma_f32_16x16x32_bf16(Bt[n][k], At[m][k], acc[ai][bj][m][n], 0, 0, 0); __builtin_amdgcn_s_setprio(0); } while (0)
; #define PG8_WAIT_V(n) asm volatile("s_waitcnt vmcnt(" #n ")" ::: "memory")
; #define PG8_WAIT_L(n) asm volatile("s_waitcnt lgkmcnt(" #n ")" ::: "memory")
; #define PG8_BAR __builtin_amdgcn_s_barrier()
; #define PG8_SCHED __builtin_amdgcn_sched_barrier(0)
; template <class Epi, class Sched, bool ALIGN_EPI = false, bool SP2 = false>
; __device__ __forceinline__ void gemm_phase(PG8_LAS unsigned char* lds, const Gemm g, const Sched& S, const Epi& E) {
;     ...
;             PG8_WAIT_V(8); PG8_WAIT_L(0); PG8_BAR; PG8_MMA(1, 0, At, B0); PG8_MMA(1, 1, At, B1); PG8_BAR; PG8_SCHED;
;             PG8_LDB(B0, 1, 0); PG8_LDB(B1, 1, 1); PG8_SCHED; PG8_LDA(At, 1, 0); PG8_STAGE(PG8_SA(0, 1), a2 + hstep, voffA);
;             PG8_WAIT_V(8); PG8_WAIT_L(0); PG8_BAR; PG8_MMA(0, 0, At, B0); PG8_MMA(0, 1, At, B1); PG8_BAR; PG8_SCHED;
	v_mfma_f32_16x16x32_bf16 v[64:67], v[116:119], v[174:177], v[64:67]
	v_mfma_f32_16x16x32_bf16 v[60:63], v[124:127], v[174:177], v[60:63]
	v_mfma_f32_16x16x32_bf16 v[48:51], v[116:119], v[186:189], v[48:51]
	v_mfma_f32_16x16x32_bf16 v[44:47], v[124:127], v[186:189], v[44:47]
	v_mfma_f32_16x16x32_bf16 v[32:35], v[116:119], v[194:197], v[32:35]
	v_mfma_f32_16x16x32_bf16 v[28:31], v[124:127], v[194:197], v[28:31]
	v_mfma_f32_16x16x32_bf16 v[16:19], v[116:119], v[202:205], v[16:19]
	v_mfma_f32_16x16x32_bf16 v[12:15], v[124:127], v[202:205], v[12:15]
	v_mfma_f32_16x16x32_bf16 v[64:67], v[120:123], v[182:185], v[64:67]
	v_mfma_f32_16x16x32_bf16 v[60:63], v[128:131], v[182:185], v[60:63]
	v_mfma_f32_16x16x32_bf16 v[48:51], v[120:123], v[190:193], v[48:51]
	v_mfma_f32_16x16x32_bf16 v[44:47], v[128:131], v[190:193], v[44:47]
	v_mfma_f32_16x16x32_bf16 v[32:35], v[120:123], v[198:201], v[32:35]
	v_mfma_f32_16x16x32_bf16 v[28:31], v[128:131], v[198:201], v[28:31]
	v_mfma_f32_16x16x32_bf16 v[16:19], v[120:123], v[206:209], v[16:19]
	v_mfma_f32_16x16x32_bf16 v[12:15], v[128:131], v[206:209], v[12:15]
	s_setprio 0
	s_setprio 1
	v_mfma_f32_16x16x32_bf16 v[56:59], v[132:135], v[174:177], v[56:59]
	v_mfma_f32_16x16x32_bf16 v[52:55], v[166:169], v[174:177], v[52:55]
	v_mfma_f32_16x16x32_bf16 v[40:43], v[132:135], v[186:189], v[40:43]
	v_mfma_f32_16x16x32_bf16 v[36:39], v[166:169], v[186:189], v[36:39]
	v_mfma_f32_16x16x32_bf16 v[24:27], v[132:135], v[194:197], v[24:27]
	v_mfma_f32_16x16x32_bf16 v[20:23], v[166:169], v[194:197], v[20:23]
	v_mfma_f32_16x16x32_bf16 v[8:11], v[132:135], v[202:205], v[8:11]
	v_mfma_f32_16x16x32_bf16 v[4:7], v[166:169], v[202:205], v[4:7]
	v_mfma_f32_16x16x32_bf16 v[56:59], v[136:139], v[182:185], v[56:59]
	v_mfma_f32_16x16x32_bf16 v[52:55], v[170:173], v[182:185], v[52:55]
	v_mfma_f32_16x16x32_bf16 v[40:43], v[136:139], v[190:193], v[40:43]
	v_mfma_f32_16x16x32_bf16 v[36:39], v[170:173], v[190:193], v[36:39]
	v_mfma_f32_16x16x32_bf16 v[24:27], v[136:139], v[198:201], v[24:27]
	v_mfma_f32_16x16x32_bf16 v[20:23], v[170:173], v[198:201], v[20:23]
	v_mfma_f32_16x16x32_bf16 v[8:11], v[136:139], v[206:209], v[8:11]
	v_mfma_f32_16x16x32_bf16 v[4:7], v[170:173], v[206:209], v[4:7]
	s_barrier
	s_add_i32 s26, 0, 0x18000
	s_add_i32 s31, 0, 0x1c000
	v_add_u32_e32 v128, s26, v178
	v_add_u32_e32 v170, s31, v178
	ds_read_b128 v[116:119], v128
	ds_read_b128 v[120:123], v128 offset:1024
	ds_read_b128 v[124:127], v128 offset:2048
	ds_read_b128 v[128:131], v128 offset:3072
	ds_read_b128 v[132:135], v170
	ds_read_b128 v[136:139], v170 offset:1024
	ds_read_b128 v[166:169], v170 offset:2048
	ds_read_b128 v[170:173], v170 offset:3072
	s_add_u32 s44, s44, 0x80000
	s_addc_u32 s45, s45, 0
	s_mov_b32 m0, s51
	v_lshl_add_u64 v[218:219], s[44:45], 0, v[160:161]
	ds_read_b128 v[174:177], v181 offset:32768
	ds_read_b128 v[182:185], v181 offset:33792
	ds_read_b128 v[186:189], v181 offset:34816
	ds_read_b128 v[190:193], v181 offset:35840
	ds_read_b128 v[194:197], v181 offset:36864
	ds_read_b128 v[198:201], v181 offset:37888
	ds_read_b128 v[202:205], v181 offset:38912
	ds_read_b128 v[206:209], v181 offset:39936
	global_load_lds_dwordx4 v[218:219], off
	v_lshl_add_u64 v[218:219], s[44:45], 0, v[158:159]
	s_mov_b32 m0, s52
	s_nop 0
	global_load_lds_dwordx4 v[218:219], off
	s_setprio 0
	s_waitcnt vmcnt(8)
	s_waitcnt lgkmcnt(0)
	s_setprio 1
	s_barrier
	v_mfma_f32_16x16x32_bf16 v[152:155], v[116:119], v[174:177], v[152:155]
	v_mfma_f32_16x16x32_bf16 v[148:151], v[124:127], v[174:177], v[148:151]
	v_mfma_f32_16x16x32_bf16 v[112:115], v[116:119], v[186:189], v[112:115]
	v_mfma_f32_16x16x32_bf16 v[108:111], v[124:127], v[186:189], v[108:111]
	v_mfma_f32_16x16x32_bf16 v[96:99], v[116:119], v[194:197], v[96:99]
	v_mfma_f32_16x16x32_bf16 v[92:95], v[124:127], v[194:197], v[92:95]
	v_mfma_f32_16x16x32_bf16 v[80:83], v[116:119], v[202:205], v[80:83]
	v_mfma_f32_16x16x32_bf16 v[76:79], v[124:127], v[202:205], v[76:79]
	v_mfma_f32_16x16x32_bf16 v[152:155], v[120:123], v[182:185], v[152:155]
	v_mfma_f32_16x16x32_bf16 v[148:151], v[128:131], v[182:185], v[148:151]
	v_mfma_f32_16x16x32_bf16 v[112:115], v[120:123], v[190:193], v[112:115]
	v_mfma_f32_16x16x32_bf16 v[108:111], v[128:131], v[190:193], v[108:111]
	v_mfma_f32_16x16x32_bf16 v[96:99], v[120:123], v[198:201], v[96:99]
	v_mfma_f32_16x16x32_bf16 v[92:95], v[128:131], v[198:201], v[92:95]
	v_mfma_f32_16x16x32_bf16 v[80:83], v[120:123], v[206:209], v[80:83]
	v_mfma_f32_16x16x32_bf16 v[76:79], v[128:131], v[206:209], v[76:79]
	s_setprio 0
	s_setprio 1
	v_mfma_f32_16x16x32_bf16 v[144:147], v[132:135], v[174:177], v[144:147]
	v_mfma_f32_16x16x32_bf16 v[140:143], v[166:169], v[174:177], v[140:143]
	v_mfma_f32_16x16x32_bf16 v[104:107], v[132:135], v[186:189], v[104:107]
	v_mfma_f32_16x16x32_bf16 v[100:103], v[166:169], v[186:189], v[100:103]
	v_mfma_f32_16x16x32_bf16 v[88:91], v[132:135], v[194:197], v[88:91]
	v_mfma_f32_16x16x32_bf16 v[84:87], v[166:169], v[194:197], v[84:87]
	v_mfma_f32_16x16x32_bf16 v[72:75], v[132:135], v[202:205], v[72:75]
	v_mfma_f32_16x16x32_bf16 v[68:71], v[166:169], v[202:205], v[68:71]
	v_mfma_f32_16x16x32_bf16 v[144:147], v[136:139], v[182:185], v[144:147]
	v_mfma_f32_16x16x32_bf16 v[140:143], v[170:173], v[182:185], v[140:143]
	v_mfma_f32_16x16x32_bf16 v[104:107], v[136:139], v[190:193], v[104:107]
	v_mfma_f32_16x16x32_bf16 v[100:103], v[170:173], v[190:193], v[100:103]
	v_mfma_f32_16x16x32_bf16 v[88:91], v[136:139], v[198:201], v[88:91]
	v_mfma_f32_16x16x32_bf16 v[84:87], v[170:173], v[198:201], v[84:87]
	v_mfma_f32_16x16x32_bf16 v[72:75], v[136:139], v[206:209], v[72:75]
	v_mfma_f32_16x16x32_bf16 v[68:71], v[170:173], v[206:209], v[68:71]
	s_barrier
; #define PG8_STAGE(bufoff, gbase, voff) do { _Pragma("unroll") for (int _i = 0; _i < 2; ++_i) \
;         __builtin_amdgcn_global_load_lds((const unsigned*)((const char*)(gbase) + (voff)[_i]), (PG8_LAS unsigned*)(lds + (bufoff) + ldsw + _i * 8192), 16, 0, 0); } while (0)
; #define PG8_LDA(dst, b, h) do { _Pragma("unroll") for (int m = 0; m < 4; ++m) _Pragma("unroll") for (int k = 0; k < 2; ++k) dst[m][k] = *(const PG8_LAS bf16x8*)(lds + PG8_SA(b, h) + aoff + m * 2048 + k * 1024); } while (0)
; #define PG8_MMA(ai, bj, At, Bt) do { __builtin_amdgcn_s_setprio(1); _Pragma("unroll") for (int m = 0; m < 4; ++m) _Pragma("unroll") for (int n = 0; n < 2; ++n) _Pragma("unroll") for (int k = 0; k < 2; ++k) \
;         acc[ai][bj][m][n] = __builtin_amdgcn_mfma_f32_16x16x32_bf16(Bt[n][k], At[m][k], acc[ai][bj][m][n], 0, 0, 0); __builtin_amdgcn_s_setprio(0); } while (0)
; #define PG8_WAIT_V(n) asm volatile("s_waitcnt vmcnt(" #n ")" ::: "memory")
; #define PG8_WAIT_L(n) asm volatile("s_waitcnt lgkmcnt(" #n ")" ::: "memory")
; #define PG8_BAR __builtin_amdgcn_s_barrier()
; #define PG8_SCHED __builtin_amdgcn_sched_barrier(0)
; template <class Epi, class Sched, bool ALIGN_EPI = false, bool SP2 = false>
; __device__ __forceinline__ void gemm_phase(PG8_LAS unsigned char* lds, const Gemm g, const Sched& S, const Epi& E) {
;     ...
;             PG8_LDA(At, 1, 1); PG8_STAGE(PG8_SB(1, 0), b3, voffB); PG8_STAGE(PG8_SB(1, 1), b3 + hstep, voffB); PG8_STAGE(PG8_SA(1, 0), a3, voffA);
;             PG8_WAIT_V(8); PG8_WAIT_L(0); PG8_BAR; PG8_MMA(1, 0, At, B0); PG8_MMA(1, 1, At, B1); PG8_BAR; PG8_SCHED;
	s_add_i32 s26, s26, s46
	v_lshl_add_u64 v[210:211], v[210:211], 0, s[60:61]
	s_mov_b32 m0, s26
	ds_read_b128 v[174:177], v181 offset:49152
	ds_read_b128 v[182:185], v181 offset:50176
	ds_read_b128 v[186:189], v181 offset:51200
	ds_read_b128 v[190:193], v181 offset:52224
	ds_read_b128 v[194:197], v181 offset:53248
	ds_read_b128 v[198:201], v181 offset:54272
	ds_read_b128 v[202:205], v181 offset:55296
	ds_read_b128 v[206:209], v181 offset:56320
	global_load_lds_dwordx4 v[210:211], off
	s_add_i32 m0, s26, 0x2000
	s_add_u32 s42, s42, 0x80080
	v_lshl_add_u64 v[210:211], v[212:213], 0, s[60:61]
	s_addc_u32 s43, s43, 0
	s_add_i32 s26, s31, s46
	global_load_lds_dwordx4 v[210:211], off
	v_lshl_add_u64 v[210:211], s[42:43], 0, v[2:3]
	s_mov_b32 m0, s26
	s_nop 0
	global_load_lds_dwordx4 v[210:211], off
	v_lshl_add_u64 v[210:211], s[42:43], 0, v[156:157]
	s_add_i32 m0, s26, 0x2000
	s_nop 0
	global_load_lds_dwordx4 v[210:211], off
	v_lshl_add_u64 v[210:211], v[214:215], 0, s[60:61]
	s_mov_b32 m0, s54
	s_nop 0
	global_load_lds_dwordx4 v[210:211], off
	v_lshl_add_u64 v[210:211], v[216:217], 0, s[60:61]
	s_mov_b32 m0, s55
	s_nop 0
	global_load_lds_dwordx4 v[210:211], off
	s_setprio 0
	s_waitcnt vmcnt(8)
	s_waitcnt lgkmcnt(0)
	s_setprio 1
	s_barrier
	v_mfma_f32_16x16x32_bf16 v[64:67], v[116:119], v[174:177], v[64:67]
	v_mfma_f32_16x16x32_bf16 v[60:63], v[124:127], v[174:177], v[60:63]
	v_mfma_f32_16x16x32_bf16 v[48:51], v[116:119], v[186:189], v[48:51]
	v_mfma_f32_16x16x32_bf16 v[44:47], v[124:127], v[186:189], v[44:47]
	v_mfma_f32_16x16x32_bf16 v[32:35], v[116:119], v[194:197], v[32:35]
	v_mfma_f32_16x16x32_bf16 v[28:31], v[124:127], v[194:197], v[28:31]
	v_mfma_f32_16x16x32_bf16 v[16:19], v[116:119], v[202:205], v[16:19]
	v_mfma_f32_16x16x32_bf16 v[12:15], v[124:127], v[202:205], v[12:15]
	v_mfma_f32_16x16x32_bf16 v[64:67], v[120:123], v[182:185], v[64:67]
	v_mfma_f32_16x16x32_bf16 v[60:63], v[128:131], v[182:185], v[60:63]
	v_mfma_f32_16x16x32_bf16 v[48:51], v[120:123], v[190:193], v[48:51]
	v_mfma_f32_16x16x32_bf16 v[44:47], v[128:131], v[190:193], v[44:47]
	v_mfma_f32_16x16x32_bf16 v[32:35], v[120:123], v[198:201], v[32:35]
	v_mfma_f32_16x16x32_bf16 v[28:31], v[128:131], v[198:201], v[28:31]
	v_mfma_f32_16x16x32_bf16 v[16:19], v[120:123], v[206:209], v[16:19]
	v_mfma_f32_16x16x32_bf16 v[12:15], v[128:131], v[206:209], v[12:15]
	s_setprio 0
	s_setprio 1
	v_mfma_f32_16x16x32_bf16 v[56:59], v[132:135], v[174:177], v[56:59]
	v_mfma_f32_16x16x32_bf16 v[52:55], v[166:169], v[174:177], v[52:55]
	v_mfma_f32_16x16x32_bf16 v[40:43], v[132:135], v[186:189], v[40:43]
	v_mfma_f32_16x16x32_bf16 v[36:39], v[166:169], v[186:189], v[36:39]
	v_mfma_f32_16x16x32_bf16 v[24:27], v[132:135], v[194:197], v[24:27]
	v_mfma_f32_16x16x32_bf16 v[20:23], v[166:169], v[194:197], v[20:23]
	v_mfma_f32_16x16x32_bf16 v[8:11], v[132:135], v[202:205], v[8:11]
	v_mfma_f32_16x16x32_bf16 v[4:7], v[166:169], v[202:205], v[4:7]
	v_mfma_f32_16x16x32_bf16 v[56:59], v[136:139], v[182:185], v[56:59]
	v_mfma_f32_16x16x32_bf16 v[52:55], v[170:173], v[182:185], v[52:55]
	v_mfma_f32_16x16x32_bf16 v[40:43], v[136:139], v[190:193], v[40:43]
	v_mfma_f32_16x16x32_bf16 v[36:39], v[170:173], v[190:193], v[36:39]
	v_mfma_f32_16x16x32_bf16 v[24:27], v[136:139], v[198:201], v[24:27]
	v_mfma_f32_16x16x32_bf16 v[20:23], v[170:173], v[198:201], v[20:23]
	v_mfma_f32_16x16x32_bf16 v[8:11], v[136:139], v[206:209], v[8:11]
	v_mfma_f32_16x16x32_bf16 v[4:7], v[170:173], v[206:209], v[4:7]
	s_barrier
	s_add_i32 s66, s66, 2
	s_add_u32 s38, s38, 0x100
	s_addc_u32 s39, s39, 0
	s_add_u32 s63, s63, 0x100
	s_addc_u32 s64, s64, 0
	s_cmp_gt_u32 s66, 29
	s_cbranch_scc0 .LBB0_1961
	s_and_b64 vcc, exec, s[16:17]
	s_cbranch_vccz .LBB0_1964
	s_barrier

; #define PG8_STAGE(bufoff, gbase, voff) do { _Pragma("unroll") for (int _i = 0; _i < 2; ++_i) \
;         __builtin_amdgcn_global_load_lds((const unsigned*)((const char*)(gbase) + (voff)[_i]), (PG8_LAS unsigned*)(lds + (bufoff) + ldsw + _i * 8192), 16, 0, 0); } while (0)
; #define PG8_LDA(dst, b, h) do { _Pragma("unroll") for (int m = 0; m < 4; ++m) _Pragma("unroll") for (int k = 0; k < 2; ++k) dst[m][k] = *(const PG8_LAS bf16x8*)(lds + PG8_SA(b, h) + aoff + m * 2048 + k * 1024); } while (0)
; #define PG8_LDB(dst, b, h) do { _Pragma("unroll") for (int n = 0; n < 2; ++n) _Pragma("unroll") for (int k = 0; k < 2; ++k) dst[n][k] = *(const PG8_LAS bf16x8*)(lds + PG8_SB(b, h) + boff + n * 2048 + k * 1024); } while (0)
; #define PG8_MMA(ai, bj, At, Bt) do { __builtin_amdgcn_s_setprio(1); _Pragma("unroll") for (int m = 0; m < 4; ++m) _Pragma("unroll") for (int n = 0; n < 2; ++n) _Pragma("unroll") for (int k = 0; k < 2; ++k) \
;         acc[ai][bj][m][n] = __builtin_amdgcn_mfma_f32_16x16x32_bf16(Bt[n][k], At[m][k], acc[ai][bj][m][n], 0, 0, 0); __builtin_amdgcn_s_setprio(0); } while (0)
; #define PG8_WAIT_V(n) asm volatile("s_waitcnt vmcnt(" #n ")" ::: "memory")
; #define PG8_WAIT_L(n) asm volatile("s_waitcnt lgkmcnt(" #n ")" ::: "memory")
; template <class Epi, class Sched, bool ALIGN_EPI = false, bool SP2 = false>
; __device__ __forceinline__ void gemm_phase(PG8_LAS unsigned char* lds, const Gemm g, const Sched& S, const Epi& E) {
;     ...
;             const bool last = (t == nt - 2);
;             const char* a1 = cA + (size_t)(t + 1) * kstep;
;             const char* a2 = last ? nA : cA + (size_t)(t + 2) * kstep; const char* b2 = last ? nB : cB + (size_t)(t + 2) * kstep;
;             const char* a3 = a2 + kstep; const char* b3 = b2 + kstep;
;             if (last && has_next) S.a_ready(nxt);
;             if constexpr (SP2) {
;             PG8_LDB(B0, 0, 0); PG8_LDB(B1, 0, 1); PG8_SCHED; PG8_LDA(At, 0, 0); PG8_STAGE(PG8_SA(1, 1), a1 + hstep, voffA);
;             PG8_WAIT_V(8); PG8_WAIT_L(0); PG8_BAR; PG8_MMA(0, 0, At, B0); PG8_MMA(0, 1, At, B1); PG8_BAR; PG8_SCHED;
;             PG8_LDA(At, 0, 1); PG8_STAGE(PG8_SB(0, 0), b2, voffB); PG8_STAGE(PG8_SB(0, 1), b2 + hstep, voffB); PG8_STAGE(PG8_SA(0, 0), a2, voffA);
;             PG8_WAIT_V(8); PG8_WAIT_L(0); PG8_BAR; PG8_MMA(1, 0, At, B0); PG8_MMA(1, 1, At, B1); PG8_BAR; PG8_SCHED;
.LBB0_2104:
	s_add_u32 s26, s34, 0xfff80080
	s_addc_u32 s31, s35, -1
	s_add_i32 s57, 0, 0x10000
	s_cmp_eq_u32 s56, 28
	s_cselect_b32 s39, s17, s31
	s_cselect_b32 s38, s52, s26
	v_add_u32_e32 v149, s57, v146
	s_cselect_b32 s37, s15, s55
	s_cselect_b32 s36, s53, s54
	s_add_i32 s26, 0, 0x14000
	ds_read_b128 v[142:145], v149
	ds_read_b128 v[150:153], v149 offset:1024
	ds_read_b128 v[154:157], v149 offset:2048
	ds_read_b128 v[158:161], v149 offset:3072
	v_add_u32_e32 v149, s26, v146
	ds_read_b128 v[162:165], v149
	ds_read_b128 v[166:169], v149 offset:1024
	ds_read_b128 v[170:173], v149 offset:2048
	ds_read_b128 v[174:177], v149 offset:3072
	v_lshl_add_u64 v[178:179], s[34:35], 0, v[138:139]
	s_add_i32 m0, s43, 0xc000
	ds_read_b128 v[182:185], v148
	ds_read_b128 v[186:189], v148 offset:1024
	ds_read_b128 v[190:193], v148 offset:2048
	ds_read_b128 v[194:197], v148 offset:3072
	ds_read_b128 v[198:201], v148 offset:4096
	ds_read_b128 v[202:205], v148 offset:5120
	ds_read_b128 v[206:209], v148 offset:6144
	ds_read_b128 v[210:213], v148 offset:7168
	global_load_lds_dwordx4 v[178:179], off
	v_lshl_add_u64 v[178:179], s[34:35], 0, v[140:141]
	s_add_i32 m0, s43, 0xe000
	s_nop 0
	global_load_lds_dwordx4 v[178:179], off
	s_setprio 0
	s_waitcnt vmcnt(8)
	s_waitcnt lgkmcnt(0)
	s_setprio 1
	s_barrier
	v_mfma_f32_16x16x32_bf16 v[128:131], v[142:145], v[182:185], v[128:131]
	v_mfma_f32_16x16x32_bf16 v[124:127], v[154:157], v[182:185], v[124:127]
	v_mfma_f32_16x16x32_bf16 v[112:115], v[142:145], v[190:193], v[112:115]
	v_mfma_f32_16x16x32_bf16 v[108:111], v[154:157], v[190:193], v[108:111]
	v_mfma_f32_16x16x32_bf16 v[96:99], v[142:145], v[198:201], v[96:99]
	v_mfma_f32_16x16x32_bf16 v[92:95], v[154:157], v[198:201], v[92:95]
	v_mfma_f32_16x16x32_bf16 v[80:83], v[142:145], v[206:209], v[80:83]
	v_mfma_f32_16x16x32_bf16 v[76:79], v[154:157], v[206:209], v[76:79]
	v_mfma_f32_16x16x32_bf16 v[128:131], v[150:153], v[186:189], v[128:131]
	v_mfma_f32_16x16x32_bf16 v[124:127], v[158:161], v[186:189], v[124:127]
	v_mfma_f32_16x16x32_bf16 v[112:115], v[150:153], v[194:197], v[112:115]
	v_mfma_f32_16x16x32_bf16 v[108:111], v[158:161], v[194:197], v[108:111]
	v_mfma_f32_16x16x32_bf16 v[96:99], v[150:153], v[202:205], v[96:99]
	v_mfma_f32_16x16x32_bf16 v[92:95], v[158:161], v[202:205], v[92:95]
	v_mfma_f32_16x16x32_bf16 v[80:83], v[150:153], v[210:213], v[80:83]
	v_mfma_f32_16x16x32_bf16 v[76:79], v[158:161], v[210:213], v[76:79]
	s_setprio 0
	s_setprio 1
	v_mfma_f32_16x16x32_bf16 v[120:123], v[162:165], v[182:185], v[120:123]
	v_mfma_f32_16x16x32_bf16 v[116:119], v[170:173], v[182:185], v[116:119]
	v_mfma_f32_16x16x32_bf16 v[104:107], v[162:165], v[190:193], v[104:107]
	v_mfma_f32_16x16x32_bf16 v[100:103], v[170:173], v[190:193], v[100:103]
	v_mfma_f32_16x16x32_bf16 v[88:91], v[162:165], v[198:201], v[88:91]
	v_mfma_f32_16x16x32_bf16 v[84:87], v[170:173], v[198:201], v[84:87]
	v_mfma_f32_16x16x32_bf16 v[72:75], v[162:165], v[206:209], v[72:75]
	v_mfma_f32_16x16x32_bf16 v[68:71], v[170:173], v[206:209], v[68:71]
	v_mfma_f32_16x16x32_bf16 v[120:123], v[166:169], v[186:189], v[120:123]
	v_mfma_f32_16x16x32_bf16 v[116:119], v[174:177], v[186:189], v[116:119]
	v_mfma_f32_16x16x32_bf16 v[104:107], v[166:169], v[194:197], v[104:107]
	v_mfma_f32_16x16x32_bf16 v[100:103], v[174:177], v[194:197], v[100:103]
	v_mfma_f32_16x16x32_bf16 v[88:91], v[166:169], v[202:205], v[88:91]
	v_mfma_f32_16x16x32_bf16 v[84:87], v[174:177], v[202:205], v[84:87]
	v_mfma_f32_16x16x32_bf16 v[72:75], v[166:169], v[210:213], v[72:75]
	v_mfma_f32_16x16x32_bf16 v[68:71], v[174:177], v[210:213], v[68:71]
	s_barrier
	s_add_i32 s31, s57, s42
	v_lshl_add_u64 v[178:179], s[36:37], 0, v[2:3]
	s_mov_b32 m0, s31
	ds_read_b128 v[182:185], v148 offset:16384
	ds_read_b128 v[186:189], v148 offset:17408
	ds_read_b128 v[190:193], v148 offset:18432
	ds_read_b128 v[194:197], v148 offset:19456
	ds_read_b128 v[198:201], v148 offset:20480
	ds_read_b128 v[202:205], v148 offset:21504
	ds_read_b128 v[206:209], v148 offset:22528
	ds_read_b128 v[210:213], v148 offset:23552
	global_load_lds_dwordx4 v[178:179], off
	s_add_i32 m0, s31, 0x2000
	s_add_u32 s62, s36, 0x80000
	v_lshl_add_u64 v[214:215], s[36:37], 0, v[132:133]
	s_addc_u32 s63, s37, 0
	s_add_i32 s26, s26, s42
	global_load_lds_dwordx4 v[214:215], off
	v_lshl_add_u64 v[216:217], s[62:63], 0, v[2:3]
	s_mov_b32 m0, s26
	v_lshl_add_u64 v[218:219], s[38:39], 0, v[134:135]
	global_load_lds_dwordx4 v[216:217], off
	v_lshl_add_u64 v[216:217], s[62:63], 0, v[132:133]
	s_add_i32 m0, s26, 0x2000
	s_nop 0
	global_load_lds_dwordx4 v[216:217], off
	v_lshl_add_u64 v[216:217], s[38:39], 0, v[136:137]
	s_mov_b32 m0, s43
	s_nop 0
	global_load_lds_dwordx4 v[216:217], off
	s_mov_b32 m0, s44
	s_nop 0
	global_load_lds_dwordx4 v[218:219], off
	s_setprio 0
	s_waitcnt vmcnt(8)
	s_waitcnt lgkmcnt(0)
	s_setprio 1
	s_barrier
; #define PG8_STAGE(bufoff, gbase, voff) do { _Pragma("unroll") for (int _i = 0; _i < 2; ++_i) \
;         __builtin_amdgcn_global_load_lds((const unsigned*)((const char*)(gbase) + (voff)[_i]), (PG8_LAS unsigned*)(lds + (bufoff) + ldsw + _i * 8192), 16, 0, 0); } while (0)
; #define PG8_LDA(dst, b, h) do { _Pragma("unroll") for (int m = 0; m < 4; ++m) _Pragma("unroll") for (int k = 0; k < 2; ++k) dst[m][k] = *(const PG8_LAS bf16x8*)(lds + PG8_SA(b, h) + aoff + m * 2048 + k * 1024); } while (0)
; #define PG8_LDB(dst, b, h) do { _Pragma("unroll") for (int n = 0; n < 2; ++n) _Pragma("unroll") for (int k = 0; k < 2; ++k) dst[n][k] = *(const PG8_LAS bf16x8*)(lds + PG8_SB(b, h) + boff + n * 2048 + k * 1024); } while (0)
; #define PG8_MMA(ai, bj, At, Bt) do { __builtin_amdgcn_s_setprio(1); _Pragma("unroll") for (int m = 0; m < 4; ++m) _Pragma("unroll") for (int n = 0; n < 2; ++n) _Pragma("unroll") for (int k = 0; k < 2; ++k) \
;         acc[ai][bj][m][n] = __builtin_amdgcn_mfma_f32_16x16x32_bf16(Bt[n][k], At[m][k], acc[ai][bj][m][n], 0, 0, 0); __builtin_amdgcn_s_setprio(0); } while (0)
; #define PG8_WAIT_V(n) asm volatile("s_waitcnt vmcnt(" #n ")" ::: "memory")
; #define PG8_WAIT_L(n) asm volatile("s_waitcnt lgkmcnt(" #n ")" ::: "memory")
; #define PG8_BAR __builtin_amdgcn_s_barrier()
; #define PG8_SCHED __builtin_amdgcn_sched_barrier(0)
; template <class Epi, class Sched, bool ALIGN_EPI = false, bool SP2 = false>
; __device__ __forceinline__ void gemm_phase(PG8_LAS unsigned char* lds, const Gemm g, const Sched& S, const Epi& E) {
;     ...
;             PG8_WAIT_V(8); PG8_WAIT_L(0); PG8_BAR; PG8_MMA(1, 0, At, B0); PG8_MMA(1, 1, At, B1); PG8_BAR; PG8_SCHED;
;             PG8_LDB(B0, 1, 0); PG8_LDB(B1, 1, 1); PG8_SCHED; PG8_LDA(At, 1, 0); PG8_STAGE(PG8_SA(0, 1), a2 + hstep, voffA);
;             PG8_WAIT_V(8); PG8_WAIT_L(0); PG8_BAR; PG8_MMA(0, 0, At, B0); PG8_MMA(0, 1, At, B1); PG8_BAR; PG8_SCHED;
	v_mfma_f32_16x16x32_bf16 v[64:67], v[142:145], v[182:185], v[64:67]
	v_mfma_f32_16x16x32_bf16 v[60:63], v[154:157], v[182:185], v[60:63]
	v_mfma_f32_16x16x32_bf16 v[48:51], v[142:145], v[190:193], v[48:51]
	v_mfma_f32_16x16x32_bf16 v[44:47], v[154:157], v[190:193], v[44:47]
	v_mfma_f32_16x16x32_bf16 v[32:35], v[142:145], v[198:201], v[32:35]
	v_mfma_f32_16x16x32_bf16 v[28:31], v[154:157], v[198:201], v[28:31]
	v_mfma_f32_16x16x32_bf16 v[16:19], v[142:145], v[206:209], v[16:19]
	v_mfma_f32_16x16x32_bf16 v[12:15], v[154:157], v[206:209], v[12:15]
	v_mfma_f32_16x16x32_bf16 v[64:67], v[150:153], v[186:189], v[64:67]
	v_mfma_f32_16x16x32_bf16 v[60:63], v[158:161], v[186:189], v[60:63]
	v_mfma_f32_16x16x32_bf16 v[48:51], v[150:153], v[194:197], v[48:51]
	v_mfma_f32_16x16x32_bf16 v[44:47], v[158:161], v[194:197], v[44:47]
	v_mfma_f32_16x16x32_bf16 v[32:35], v[150:153], v[202:205], v[32:35]
	v_mfma_f32_16x16x32_bf16 v[28:31], v[158:161], v[202:205], v[28:31]
	v_mfma_f32_16x16x32_bf16 v[16:19], v[150:153], v[210:213], v[16:19]
	v_mfma_f32_16x16x32_bf16 v[12:15], v[158:161], v[210:213], v[12:15]
	s_setprio 0
	s_setprio 1
	v_mfma_f32_16x16x32_bf16 v[56:59], v[162:165], v[182:185], v[56:59]
	v_mfma_f32_16x16x32_bf16 v[52:55], v[170:173], v[182:185], v[52:55]
	v_mfma_f32_16x16x32_bf16 v[40:43], v[162:165], v[190:193], v[40:43]
	v_mfma_f32_16x16x32_bf16 v[36:39], v[170:173], v[190:193], v[36:39]
	v_mfma_f32_16x16x32_bf16 v[24:27], v[162:165], v[198:201], v[24:27]
	v_mfma_f32_16x16x32_bf16 v[20:23], v[170:173], v[198:201], v[20:23]
	v_mfma_f32_16x16x32_bf16 v[8:11], v[162:165], v[206:209], v[8:11]
	v_mfma_f32_16x16x32_bf16 v[4:7], v[170:173], v[206:209], v[4:7]
	v_mfma_f32_16x16x32_bf16 v[56:59], v[166:169], v[186:189], v[56:59]
	v_mfma_f32_16x16x32_bf16 v[52:55], v[174:177], v[186:189], v[52:55]
	v_mfma_f32_16x16x32_bf16 v[40:43], v[166:169], v[194:197], v[40:43]
	v_mfma_f32_16x16x32_bf16 v[36:39], v[174:177], v[194:197], v[36:39]
	v_mfma_f32_16x16x32_bf16 v[24:27], v[166:169], v[202:205], v[24:27]
	v_mfma_f32_16x16x32_bf16 v[20:23], v[174:177], v[202:205], v[20:23]
	v_mfma_f32_16x16x32_bf16 v[8:11], v[166:169], v[210:213], v[8:11]
	v_mfma_f32_16x16x32_bf16 v[4:7], v[174:177], v[210:213], v[4:7]
	s_barrier
	s_add_i32 s26, 0, 0x18000
	v_add_u32_e32 v149, s26, v146
	s_add_i32 s31, 0, 0x1c000
	ds_read_b128 v[142:145], v149
	ds_read_b128 v[150:153], v149 offset:1024
	ds_read_b128 v[154:157], v149 offset:2048
	ds_read_b128 v[158:161], v149 offset:3072
	v_add_u32_e32 v149, s31, v146
	ds_read_b128 v[162:165], v149
	ds_read_b128 v[166:169], v149 offset:1024
	ds_read_b128 v[170:173], v149 offset:2048
	ds_read_b128 v[174:177], v149 offset:3072
	s_add_u32 s38, s38, 0x80000
	s_addc_u32 s39, s39, 0
	s_mov_b32 m0, s45
	v_lshl_add_u64 v[220:221], s[38:39], 0, v[136:137]
	ds_read_b128 v[182:185], v148 offset:32768
	ds_read_b128 v[186:189], v148 offset:33792
	ds_read_b128 v[190:193], v148 offset:34816
	ds_read_b128 v[194:197], v148 offset:35840
	ds_read_b128 v[198:201], v148 offset:36864
	ds_read_b128 v[202:205], v148 offset:37888
	ds_read_b128 v[206:209], v148 offset:38912
	ds_read_b128 v[210:213], v148 offset:39936
	global_load_lds_dwordx4 v[220:221], off
	v_lshl_add_u64 v[220:221], s[38:39], 0, v[134:135]
	s_mov_b32 m0, s46
	s_nop 0
	global_load_lds_dwordx4 v[220:221], off
	s_setprio 0
	s_waitcnt vmcnt(8)
	s_waitcnt lgkmcnt(0)
	s_setprio 1
	s_barrier
	v_mfma_f32_16x16x32_bf16 v[128:131], v[142:145], v[182:185], v[128:131]
	v_mfma_f32_16x16x32_bf16 v[124:127], v[154:157], v[182:185], v[124:127]
	v_mfma_f32_16x16x32_bf16 v[112:115], v[142:145], v[190:193], v[112:115]
	v_mfma_f32_16x16x32_bf16 v[108:111], v[154:157], v[190:193], v[108:111]
	v_mfma_f32_16x16x32_bf16 v[96:99], v[142:145], v[198:201], v[96:99]
	v_mfma_f32_16x16x32_bf16 v[92:95], v[154:157], v[198:201], v[92:95]
	v_mfma_f32_16x16x32_bf16 v[80:83], v[142:145], v[206:209], v[80:83]
	v_mfma_f32_16x16x32_bf16 v[76:79], v[154:157], v[206:209], v[76:79]
	v_mfma_f32_16x16x32_bf16 v[128:131], v[150:153], v[186:189], v[128:131]
	v_mfma_f32_16x16x32_bf16 v[124:127], v[158:161], v[186:189], v[124:127]
	v_mfma_f32_16x16x32_bf16 v[112:115], v[150:153], v[194:197], v[112:115]
	v_mfma_f32_16x16x32_bf16 v[108:111], v[158:161], v[194:197], v[108:111]
	v_mfma_f32_16x16x32_bf16 v[96:99], v[150:153], v[202:205], v[96:99]
	v_mfma_f32_16x16x32_bf16 v[92:95], v[158:161], v[202:205], v[92:95]
	v_mfma_f32_16x16x32_bf16 v[80:83], v[150:153], v[210:213], v[80:83]
	v_mfma_f32_16x16x32_bf16 v[76:79], v[158:161], v[210:213], v[76:79]
	s_setprio 0
	s_setprio 1
	v_mfma_f32_16x16x32_bf16 v[120:123], v[162:165], v[182:185], v[120:123]
	v_mfma_f32_16x16x32_bf16 v[116:119], v[170:173], v[182:185], v[116:119]
	v_mfma_f32_16x16x32_bf16 v[104:107], v[162:165], v[190:193], v[104:107]
	v_mfma_f32_16x16x32_bf16 v[100:103], v[170:173], v[190:193], v[100:103]
	v_mfma_f32_16x16x32_bf16 v[88:91], v[162:165], v[198:201], v[88:91]
	v_mfma_f32_16x16x32_bf16 v[84:87], v[170:173], v[198:201], v[84:87]
	v_mfma_f32_16x16x32_bf16 v[72:75], v[162:165], v[206:209], v[72:75]
	v_mfma_f32_16x16x32_bf16 v[68:71], v[170:173], v[206:209], v[68:71]
	v_mfma_f32_16x16x32_bf16 v[120:123], v[166:169], v[186:189], v[120:123]
	v_mfma_f32_16x16x32_bf16 v[116:119], v[174:177], v[186:189], v[116:119]
	v_mfma_f32_16x16x32_bf16 v[104:107], v[166:169], v[194:197], v[104:107]
	v_mfma_f32_16x16x32_bf16 v[100:103], v[174:177], v[194:197], v[100:103]
	v_mfma_f32_16x16x32_bf16 v[88:91], v[166:169], v[202:205], v[88:91]
	v_mfma_f32_16x16x32_bf16 v[84:87], v[174:177], v[202:205], v[84:87]
	v_mfma_f32_16x16x32_bf16 v[72:75], v[166:169], v[210:213], v[72:75]
	v_mfma_f32_16x16x32_bf16 v[68:71], v[174:177], v[210:213], v[68:71]
	s_barrier
; #define PG8_STAGE(bufoff, gbase, voff) do { _Pragma("unroll") for (int _i = 0; _i < 2; ++_i) \
;         __builtin_amdgcn_global_load_lds((const unsigned*)((const char*)(gbase) + (voff)[_i]), (PG8_LAS unsigned*)(lds + (bufoff) + ldsw + _i * 8192), 16, 0, 0); } while (0)
; #define PG8_LDA(dst, b, h) do { _Pragma("unroll") for (int m = 0; m < 4; ++m) _Pragma("unroll") for (int k = 0; k < 2; ++k) dst[m][k] = *(const PG8_LAS bf16x8*)(lds + PG8_SA(b, h) + aoff + m * 2048 + k * 1024); } while (0)
; #define PG8_MMA(ai, bj, At, Bt) do { __builtin_amdgcn_s_setprio(1); _Pragma("unroll") for (int m = 0; m < 4; ++m) _Pragma("unroll") for (int n = 0; n < 2; ++n) _Pragma("unroll") for (int k = 0; k < 2; ++k) \
;         acc[ai][bj][m][n] = __builtin_amdgcn_mfma_f32_16x16x32_bf16(Bt[n][k], At[m][k], acc[ai][bj][m][n], 0, 0, 0); __builtin_amdgcn_s_setprio(0); } while (0)
; #define PG8_WAIT_V(n) asm volatile("s_waitcnt vmcnt(" #n ")" ::: "memory")
; #define PG8_WAIT_L(n) asm volatile("s_waitcnt lgkmcnt(" #n ")" ::: "memory")
; #define PG8_BAR __builtin_amdgcn_s_barrier()
; #define PG8_SCHED __builtin_amdgcn_sched_barrier(0)
; template <class Epi, class Sched, bool ALIGN_EPI = false, bool SP2 = false>
; __device__ __forceinline__ void gemm_phase(PG8_LAS unsigned char* lds, const Gemm g, const Sched& S, const Epi& E) {
;     ...
;             PG8_LDA(At, 1, 1); PG8_STAGE(PG8_SB(1, 0), b3, voffB); PG8_STAGE(PG8_SB(1, 1), b3 + hstep, voffB); PG8_STAGE(PG8_SA(1, 0), a3, voffA);
;             PG8_WAIT_V(8); PG8_WAIT_L(0); PG8_BAR; PG8_MMA(1, 0, At, B0); PG8_MMA(1, 1, At, B1); PG8_BAR; PG8_SCHED;
	s_add_i32 s26, s26, s42
	v_lshl_add_u64 v[178:179], v[178:179], 0, s[60:61]
	s_mov_b32 m0, s26
	ds_read_b128 v[182:185], v148 offset:49152
	ds_read_b128 v[186:189], v148 offset:50176
	ds_read_b128 v[190:193], v148 offset:51200
	ds_read_b128 v[194:197], v148 offset:52224
	ds_read_b128 v[198:201], v148 offset:53248
	ds_read_b128 v[202:205], v148 offset:54272
	ds_read_b128 v[206:209], v148 offset:55296
	ds_read_b128 v[210:213], v148 offset:56320
	global_load_lds_dwordx4 v[178:179], off
	s_add_i32 m0, s26, 0x2000
	s_add_u32 s36, s36, 0x80080
	v_lshl_add_u64 v[178:179], v[214:215], 0, s[60:61]
	s_addc_u32 s37, s37, 0
	s_add_i32 s26, s31, s42
	global_load_lds_dwordx4 v[178:179], off
	v_lshl_add_u64 v[178:179], s[36:37], 0, v[2:3]
	s_mov_b32 m0, s26
	s_nop 0
	global_load_lds_dwordx4 v[178:179], off
	v_lshl_add_u64 v[178:179], s[36:37], 0, v[132:133]
	s_add_i32 m0, s26, 0x2000
	s_nop 0
	global_load_lds_dwordx4 v[178:179], off
	v_lshl_add_u64 v[178:179], v[216:217], 0, s[60:61]
	s_mov_b32 m0, s47
	s_nop 0
	global_load_lds_dwordx4 v[178:179], off
	v_lshl_add_u64 v[178:179], v[218:219], 0, s[60:61]
	s_mov_b32 m0, s50
	s_nop 0
	global_load_lds_dwordx4 v[178:179], off
	s_setprio 0
	s_waitcnt vmcnt(8)
	s_waitcnt lgkmcnt(0)
	s_setprio 1
	s_barrier
	v_mfma_f32_16x16x32_bf16 v[64:67], v[142:145], v[182:185], v[64:67]
	v_mfma_f32_16x16x32_bf16 v[60:63], v[154:157], v[182:185], v[60:63]
	v_mfma_f32_16x16x32_bf16 v[48:51], v[142:145], v[190:193], v[48:51]
	v_mfma_f32_16x16x32_bf16 v[44:47], v[154:157], v[190:193], v[44:47]
	v_mfma_f32_16x16x32_bf16 v[32:35], v[142:145], v[198:201], v[32:35]
	v_mfma_f32_16x16x32_bf16 v[28:31], v[154:157], v[198:201], v[28:31]
	v_mfma_f32_16x16x32_bf16 v[16:19], v[142:145], v[206:209], v[16:19]
	v_mfma_f32_16x16x32_bf16 v[12:15], v[154:157], v[206:209], v[12:15]
	v_mfma_f32_16x16x32_bf16 v[64:67], v[150:153], v[186:189], v[64:67]
	v_mfma_f32_16x16x32_bf16 v[60:63], v[158:161], v[186:189], v[60:63]
	v_mfma_f32_16x16x32_bf16 v[48:51], v[150:153], v[194:197], v[48:51]
	v_mfma_f32_16x16x32_bf16 v[44:47], v[158:161], v[194:197], v[44:47]
	v_mfma_f32_16x16x32_bf16 v[32:35], v[150:153], v[202:205], v[32:35]
	v_mfma_f32_16x16x32_bf16 v[28:31], v[158:161], v[202:205], v[28:31]
	v_mfma_f32_16x16x32_bf16 v[16:19], v[150:153], v[210:213], v[16:19]
	v_mfma_f32_16x16x32_bf16 v[12:15], v[158:161], v[210:213], v[12:15]
	s_setprio 0
	s_setprio 1
	v_mfma_f32_16x16x32_bf16 v[56:59], v[162:165], v[182:185], v[56:59]
	v_mfma_f32_16x16x32_bf16 v[52:55], v[170:173], v[182:185], v[52:55]
	v_mfma_f32_16x16x32_bf16 v[40:43], v[162:165], v[190:193], v[40:43]
	v_mfma_f32_16x16x32_bf16 v[36:39], v[170:173], v[190:193], v[36:39]
	v_mfma_f32_16x16x32_bf16 v[24:27], v[162:165], v[198:201], v[24:27]
	v_mfma_f32_16x16x32_bf16 v[20:23], v[170:173], v[198:201], v[20:23]
	v_mfma_f32_16x16x32_bf16 v[8:11], v[162:165], v[206:209], v[8:11]
	v_mfma_f32_16x16x32_bf16 v[4:7], v[170:173], v[206:209], v[4:7]
	v_mfma_f32_16x16x32_bf16 v[56:59], v[166:169], v[186:189], v[56:59]
	v_mfma_f32_16x16x32_bf16 v[52:55], v[174:177], v[186:189], v[52:55]
	v_mfma_f32_16x16x32_bf16 v[40:43], v[166:169], v[194:197], v[40:43]
	v_mfma_f32_16x16x32_bf16 v[36:39], v[174:177], v[194:197], v[36:39]
	v_mfma_f32_16x16x32_bf16 v[24:27], v[166:169], v[202:205], v[24:27]
	v_mfma_f32_16x16x32_bf16 v[20:23], v[174:177], v[202:205], v[20:23]
	v_mfma_f32_16x16x32_bf16 v[8:11], v[166:169], v[210:213], v[8:11]
	v_mfma_f32_16x16x32_bf16 v[4:7], v[174:177], v[210:213], v[4:7]
	s_barrier
	s_add_i32 s56, s56, 2
	s_add_u32 s34, s34, 0x100
	s_addc_u32 s35, s35, 0
	s_add_u32 s54, s54, 0x100
	s_addc_u32 s55, s55, 0
	s_cmp_gt_u32 s56, 29
	s_cbranch_scc0 .LBB0_2104
	s_and_b64 vcc, exec, s[12:13]
	s_cbranch_vccz .LBB0_2107
	s_barrier

; #define PG8_STAGE(bufoff, gbase, voff) do { _Pragma("unroll") for (int _i = 0; _i < 2; ++_i) \
;         __builtin_amdgcn_global_load_lds((const unsigned*)((const char*)(gbase) + (voff)[_i]), (PG8_LAS unsigned*)(lds + (bufoff) + ldsw + _i * 8192), 16, 0, 0); } while (0)
; #define PG8_LDA(dst, b, h) do { _Pragma("unroll") for (int m = 0; m < 4; ++m) _Pragma("unroll") for (int k = 0; k < 2; ++k) dst[m][k] = *(const PG8_LAS bf16x8*)(lds + PG8_SA(b, h) + aoff + m * 2048 + k * 1024); } while (0)
; #define PG8_LDB(dst, b, h) do { _Pragma("unroll") for (int n = 0; n < 2; ++n) _Pragma("unroll") for (int k = 0; k < 2; ++k) dst[n][k] = *(const PG8_LAS bf16x8*)(lds + PG8_SB(b, h) + boff + n * 2048 + k * 1024); } while (0)
; #define PG8_MMA(ai, bj, At, Bt) do { __builtin_amdgcn_s_setprio(1); _Pragma("unroll") for (int m = 0; m < 4; ++m) _Pragma("unroll") for (int n = 0; n < 2; ++n) _Pragma("unroll") for (int k = 0; k < 2; ++k) \
;         acc[ai][bj][m][n] = __builtin_amdgcn_mfma_f32_16x16x32_bf16(Bt[n][k], At[m][k], acc[ai][bj][m][n], 0, 0, 0); __builtin_amdgcn_s_setprio(0); } while (0)
; #define PG8_WAIT_V(n) asm volatile("s_waitcnt vmcnt(" #n ")" ::: "memory")
; #define PG8_WAIT_L(n) asm volatile("s_waitcnt lgkmcnt(" #n ")" ::: "memory")
; template <class Epi, class Sched, bool ALIGN_EPI = false, bool SP2 = false>
; __device__ __forceinline__ void gemm_phase(PG8_LAS unsigned char* lds, const Gemm g, const Sched& S, const Epi& E) {
;     ...
;             const bool last = (t == nt - 2);
;             const char* a1 = cA + (size_t)(t + 1) * kstep;
;             const char* a2 = last ? nA : cA + (size_t)(t + 2) * kstep; const char* b2 = last ? nB : cB + (size_t)(t + 2) * kstep;
;             const char* a3 = a2 + kstep; const char* b3 = b2 + kstep;
;             if (last && has_next) S.a_ready(nxt);
;             if constexpr (SP2) {
;             PG8_LDB(B0, 0, 0); PG8_LDB(B1, 0, 1); PG8_SCHED; PG8_LDA(At, 0, 0); PG8_STAGE(PG8_SA(1, 1), a1 + hstep, voffA);
;             PG8_WAIT_V(8); PG8_WAIT_L(0); PG8_BAR; PG8_MMA(0, 0, At, B0); PG8_MMA(0, 1, At, B1); PG8_BAR; PG8_SCHED;
;             PG8_LDA(At, 0, 1); PG8_STAGE(PG8_SB(0, 0), b2, voffB); PG8_STAGE(PG8_SB(0, 1), b2 + hstep, voffB); PG8_STAGE(PG8_SA(0, 0), a2, voffA);
;             PG8_WAIT_V(8); PG8_WAIT_L(0); PG8_BAR; PG8_MMA(1, 0, At, B0); PG8_MMA(1, 1, At, B1); PG8_BAR; PG8_SCHED;
.LBB0_2176:
	s_add_u32 s26, s6, 0xffe00080
	s_addc_u32 s31, s7, -1
	s_add_i32 s67, 0, 0x10000
	s_cmpk_eq_i32 s74, 0x7c
	s_cselect_b32 s47, s30, s31
	s_cselect_b32 s46, s37, s26
	s_cselect_b32 s45, s35, s70
	s_cselect_b32 s44, s64, s66
	s_add_i32 s26, 0, 0x14000
	v_add_u32_e32 v144, s67, v181
	v_add_u32_e32 v170, s26, v181
	ds_read_b128 v[124:127], v144
	ds_read_b128 v[136:139], v144 offset:1024
	ds_read_b128 v[140:143], v144 offset:2048
	ds_read_b128 v[144:147], v144 offset:3072
	ds_read_b128 v[148:151], v170
	ds_read_b128 v[152:155], v170 offset:1024
	ds_read_b128 v[156:159], v170 offset:2048
	ds_read_b128 v[170:173], v170 offset:3072
	v_lshl_add_u64 v[178:179], s[6:7], 0, v[166:167]
	s_add_i32 m0, s51, 0xc000
	ds_read_b128 v[174:177], v183
	ds_read_b128 v[184:187], v183 offset:1024
	ds_read_b128 v[188:191], v183 offset:2048
	ds_read_b128 v[192:195], v183 offset:3072
	ds_read_b128 v[196:199], v183 offset:4096
	ds_read_b128 v[200:203], v183 offset:5120
	ds_read_b128 v[204:207], v183 offset:6144
	ds_read_b128 v[208:211], v183 offset:7168
	global_load_lds_dwordx4 v[178:179], off
	v_lshl_add_u64 v[178:179], s[6:7], 0, v[168:169]
	s_add_i32 m0, s51, 0xe000
	s_nop 0
	global_load_lds_dwordx4 v[178:179], off
	s_setprio 0
	s_waitcnt vmcnt(8)
	s_waitcnt lgkmcnt(0)
	s_setprio 1
	s_barrier
	v_mfma_f32_16x16x32_bf16 v[132:135], v[124:127], v[174:177], v[132:135]
	v_mfma_f32_16x16x32_bf16 v[128:131], v[140:143], v[174:177], v[128:131]
	v_mfma_f32_16x16x32_bf16 v[112:115], v[124:127], v[188:191], v[112:115]
	v_mfma_f32_16x16x32_bf16 v[108:111], v[140:143], v[188:191], v[108:111]
	v_mfma_f32_16x16x32_bf16 v[96:99], v[124:127], v[196:199], v[96:99]
	v_mfma_f32_16x16x32_bf16 v[92:95], v[140:143], v[196:199], v[92:95]
	v_mfma_f32_16x16x32_bf16 v[80:83], v[124:127], v[204:207], v[80:83]
	v_mfma_f32_16x16x32_bf16 v[76:79], v[140:143], v[204:207], v[76:79]
	v_mfma_f32_16x16x32_bf16 v[132:135], v[136:139], v[184:187], v[132:135]
	v_mfma_f32_16x16x32_bf16 v[128:131], v[144:147], v[184:187], v[128:131]
	v_mfma_f32_16x16x32_bf16 v[112:115], v[136:139], v[192:195], v[112:115]
	v_mfma_f32_16x16x32_bf16 v[108:111], v[144:147], v[192:195], v[108:111]
	v_mfma_f32_16x16x32_bf16 v[96:99], v[136:139], v[200:203], v[96:99]
	v_mfma_f32_16x16x32_bf16 v[92:95], v[144:147], v[200:203], v[92:95]
	v_mfma_f32_16x16x32_bf16 v[80:83], v[136:139], v[208:211], v[80:83]
	v_mfma_f32_16x16x32_bf16 v[76:79], v[144:147], v[208:211], v[76:79]
	s_setprio 0
	s_setprio 1
	v_mfma_f32_16x16x32_bf16 v[120:123], v[148:151], v[174:177], v[120:123]
	v_mfma_f32_16x16x32_bf16 v[116:119], v[156:159], v[174:177], v[116:119]
	v_mfma_f32_16x16x32_bf16 v[104:107], v[148:151], v[188:191], v[104:107]
	v_mfma_f32_16x16x32_bf16 v[100:103], v[156:159], v[188:191], v[100:103]
	v_mfma_f32_16x16x32_bf16 v[88:91], v[148:151], v[196:199], v[88:91]
	v_mfma_f32_16x16x32_bf16 v[84:87], v[156:159], v[196:199], v[84:87]
	v_mfma_f32_16x16x32_bf16 v[72:75], v[148:151], v[204:207], v[72:75]
	v_mfma_f32_16x16x32_bf16 v[68:71], v[156:159], v[204:207], v[68:71]
	v_mfma_f32_16x16x32_bf16 v[120:123], v[152:155], v[184:187], v[120:123]
	v_mfma_f32_16x16x32_bf16 v[116:119], v[170:173], v[184:187], v[116:119]
	v_mfma_f32_16x16x32_bf16 v[104:107], v[152:155], v[192:195], v[104:107]
	v_mfma_f32_16x16x32_bf16 v[100:103], v[170:173], v[192:195], v[100:103]
	v_mfma_f32_16x16x32_bf16 v[88:91], v[152:155], v[200:203], v[88:91]
	v_mfma_f32_16x16x32_bf16 v[84:87], v[170:173], v[200:203], v[84:87]
	v_mfma_f32_16x16x32_bf16 v[72:75], v[152:155], v[208:211], v[72:75]
	v_mfma_f32_16x16x32_bf16 v[68:71], v[170:173], v[208:211], v[68:71]
	s_barrier
	s_add_i32 s31, s67, s50
	v_lshl_add_u64 v[178:179], s[44:45], 0, v[2:3]
	s_mov_b32 m0, s31
	ds_read_b128 v[174:177], v183 offset:16384
	ds_read_b128 v[184:187], v183 offset:17408
	ds_read_b128 v[188:191], v183 offset:18432
	ds_read_b128 v[192:195], v183 offset:19456
	ds_read_b128 v[196:199], v183 offset:20480
	ds_read_b128 v[200:203], v183 offset:21504
	ds_read_b128 v[204:207], v183 offset:22528
	ds_read_b128 v[208:211], v183 offset:23552
	global_load_lds_dwordx4 v[178:179], off
	s_add_i32 m0, s31, 0x2000
	s_add_u32 s68, s44, 0x200000
	v_lshl_add_u64 v[212:213], s[44:45], 0, v[160:161]
	s_addc_u32 s69, s45, 0
	s_add_i32 s26, s26, s50
	global_load_lds_dwordx4 v[212:213], off
	v_lshl_add_u64 v[214:215], s[68:69], 0, v[2:3]
	s_mov_b32 m0, s26
	v_lshl_add_u64 v[216:217], s[46:47], 0, v[162:163]
	global_load_lds_dwordx4 v[214:215], off
	v_lshl_add_u64 v[214:215], s[68:69], 0, v[160:161]
	s_add_i32 m0, s26, 0x2000
	s_nop 0
	global_load_lds_dwordx4 v[214:215], off
	v_lshl_add_u64 v[214:215], s[46:47], 0, v[164:165]
	s_mov_b32 m0, s51
	s_nop 0
	global_load_lds_dwordx4 v[214:215], off
	s_mov_b32 m0, s52
	s_nop 0
	global_load_lds_dwordx4 v[216:217], off
	s_setprio 0
	s_waitcnt vmcnt(8)
	s_waitcnt lgkmcnt(0)
	s_setprio 1
	s_barrier
; #define PG8_STAGE(bufoff, gbase, voff) do { _Pragma("unroll") for (int _i = 0; _i < 2; ++_i) \
;         __builtin_amdgcn_global_load_lds((const unsigned*)((const char*)(gbase) + (voff)[_i]), (PG8_LAS unsigned*)(lds + (bufoff) + ldsw + _i * 8192), 16, 0, 0); } while (0)
; #define PG8_LDA(dst, b, h) do { _Pragma("unroll") for (int m = 0; m < 4; ++m) _Pragma("unroll") for (int k = 0; k < 2; ++k) dst[m][k] = *(const PG8_LAS bf16x8*)(lds + PG8_SA(b, h) + aoff + m * 2048 + k * 1024); } while (0)
; #define PG8_LDB(dst, b, h) do { _Pragma("unroll") for (int n = 0; n < 2; ++n) _Pragma("unroll") for (int k = 0; k < 2; ++k) dst[n][k] = *(const PG8_LAS bf16x8*)(lds + PG8_SB(b, h) + boff + n * 2048 + k * 1024); } while (0)
; #define PG8_MMA(ai, bj, At, Bt) do { __builtin_amdgcn_s_setprio(1); _Pragma("unroll") for (int m = 0; m < 4; ++m) _Pragma("unroll") for (int n = 0; n < 2; ++n) _Pragma("unroll") for (int k = 0; k < 2; ++k) \
;         acc[ai][bj][m][n] = __builtin_amdgcn_mfma_f32_16x16x32_bf16(Bt[n][k], At[m][k], acc[ai][bj][m][n], 0, 0, 0); __builtin_amdgcn_s_setprio(0); } while (0)
; #define PG8_WAIT_V(n) asm volatile("s_waitcnt vmcnt(" #n ")" ::: "memory")
; #define PG8_WAIT_L(n) asm volatile("s_waitcnt lgkmcnt(" #n ")" ::: "memory")
; #define PG8_BAR __builtin_amdgcn_s_barrier()
; #define PG8_SCHED __builtin_amdgcn_sched_barrier(0)
; template <class Epi, class Sched, bool ALIGN_EPI = false, bool SP2 = false>
; __device__ __forceinline__ void gemm_phase(PG8_LAS unsigned char* lds, const Gemm g, const Sched& S, const Epi& E) {
;     ...
;             PG8_WAIT_V(8); PG8_WAIT_L(0); PG8_BAR; PG8_MMA(1, 0, At, B0); PG8_MMA(1, 1, At, B1); PG8_BAR; PG8_SCHED;
;             PG8_LDB(B0, 1, 0); PG8_LDB(B1, 1, 1); PG8_SCHED; PG8_LDA(At, 1, 0); PG8_STAGE(PG8_SA(0, 1), a2 + hstep, voffA);
;             PG8_WAIT_V(8); PG8_WAIT_L(0); PG8_BAR; PG8_MMA(0, 0, At, B0); PG8_MMA(0, 1, At, B1); PG8_BAR; PG8_SCHED;
	v_mfma_f32_16x16x32_bf16 v[64:67], v[124:127], v[174:177], v[64:67]
	v_mfma_f32_16x16x32_bf16 v[60:63], v[140:143], v[174:177], v[60:63]
	v_mfma_f32_16x16x32_bf16 v[48:51], v[124:127], v[188:191], v[48:51]
	v_mfma_f32_16x16x32_bf16 v[44:47], v[140:143], v[188:191], v[44:47]
	v_mfma_f32_16x16x32_bf16 v[32:35], v[124:127], v[196:199], v[32:35]
	v_mfma_f32_16x16x32_bf16 v[28:31], v[140:143], v[196:199], v[28:31]
	v_mfma_f32_16x16x32_bf16 v[16:19], v[124:127], v[204:207], v[16:19]
	v_mfma_f32_16x16x32_bf16 v[12:15], v[140:143], v[204:207], v[12:15]
	v_mfma_f32_16x16x32_bf16 v[64:67], v[136:139], v[184:187], v[64:67]
	v_mfma_f32_16x16x32_bf16 v[60:63], v[144:147], v[184:187], v[60:63]
	v_mfma_f32_16x16x32_bf16 v[48:51], v[136:139], v[192:195], v[48:51]
	v_mfma_f32_16x16x32_bf16 v[44:47], v[144:147], v[192:195], v[44:47]
	v_mfma_f32_16x16x32_bf16 v[32:35], v[136:139], v[200:203], v[32:35]
	v_mfma_f32_16x16x32_bf16 v[28:31], v[144:147], v[200:203], v[28:31]
	v_mfma_f32_16x16x32_bf16 v[16:19], v[136:139], v[208:211], v[16:19]
	v_mfma_f32_16x16x32_bf16 v[12:15], v[144:147], v[208:211], v[12:15]
	s_setprio 0
	s_setprio 1
	v_mfma_f32_16x16x32_bf16 v[56:59], v[148:151], v[174:177], v[56:59]
	v_mfma_f32_16x16x32_bf16 v[52:55], v[156:159], v[174:177], v[52:55]
	v_mfma_f32_16x16x32_bf16 v[40:43], v[148:151], v[188:191], v[40:43]
	v_mfma_f32_16x16x32_bf16 v[36:39], v[156:159], v[188:191], v[36:39]
	v_mfma_f32_16x16x32_bf16 v[24:27], v[148:151], v[196:199], v[24:27]
	v_mfma_f32_16x16x32_bf16 v[20:23], v[156:159], v[196:199], v[20:23]
	v_mfma_f32_16x16x32_bf16 v[8:11], v[148:151], v[204:207], v[8:11]
	v_mfma_f32_16x16x32_bf16 v[4:7], v[156:159], v[204:207], v[4:7]
	v_mfma_f32_16x16x32_bf16 v[56:59], v[152:155], v[184:187], v[56:59]
	v_mfma_f32_16x16x32_bf16 v[52:55], v[170:173], v[184:187], v[52:55]
	v_mfma_f32_16x16x32_bf16 v[40:43], v[152:155], v[192:195], v[40:43]
	v_mfma_f32_16x16x32_bf16 v[36:39], v[170:173], v[192:195], v[36:39]
	v_mfma_f32_16x16x32_bf16 v[24:27], v[152:155], v[200:203], v[24:27]
	v_mfma_f32_16x16x32_bf16 v[20:23], v[170:173], v[200:203], v[20:23]
	v_mfma_f32_16x16x32_bf16 v[8:11], v[152:155], v[208:211], v[8:11]
	v_mfma_f32_16x16x32_bf16 v[4:7], v[170:173], v[208:211], v[4:7]
	s_barrier
	s_add_i32 s26, 0, 0x18000
	s_add_i32 s31, 0, 0x1c000
	v_add_u32_e32 v144, s26, v181
	v_add_u32_e32 v170, s31, v181
	ds_read_b128 v[124:127], v144
	ds_read_b128 v[136:139], v144 offset:1024
	ds_read_b128 v[140:143], v144 offset:2048
	ds_read_b128 v[144:147], v144 offset:3072
	ds_read_b128 v[148:151], v170
	ds_read_b128 v[152:155], v170 offset:1024
	ds_read_b128 v[156:159], v170 offset:2048
	ds_read_b128 v[170:173], v170 offset:3072
	s_add_u32 s46, s46, 0x200000
	s_addc_u32 s47, s47, 0
	s_mov_b32 m0, s53
	v_lshl_add_u64 v[218:219], s[46:47], 0, v[164:165]
	ds_read_b128 v[174:177], v183 offset:32768
	ds_read_b128 v[184:187], v183 offset:33792
	ds_read_b128 v[188:191], v183 offset:34816
	ds_read_b128 v[192:195], v183 offset:35840
	ds_read_b128 v[196:199], v183 offset:36864
	ds_read_b128 v[200:203], v183 offset:37888
	ds_read_b128 v[204:207], v183 offset:38912
	ds_read_b128 v[208:211], v183 offset:39936
	global_load_lds_dwordx4 v[218:219], off
	v_lshl_add_u64 v[218:219], s[46:47], 0, v[162:163]
	s_mov_b32 m0, s54
	s_nop 0
	global_load_lds_dwordx4 v[218:219], off
	s_setprio 0
	s_waitcnt vmcnt(8)
	s_waitcnt lgkmcnt(0)
	s_setprio 1
	s_barrier
	v_mfma_f32_16x16x32_bf16 v[132:135], v[124:127], v[174:177], v[132:135]
	v_mfma_f32_16x16x32_bf16 v[128:131], v[140:143], v[174:177], v[128:131]
	v_mfma_f32_16x16x32_bf16 v[112:115], v[124:127], v[188:191], v[112:115]
	v_mfma_f32_16x16x32_bf16 v[108:111], v[140:143], v[188:191], v[108:111]
	v_mfma_f32_16x16x32_bf16 v[96:99], v[124:127], v[196:199], v[96:99]
	v_mfma_f32_16x16x32_bf16 v[92:95], v[140:143], v[196:199], v[92:95]
	v_mfma_f32_16x16x32_bf16 v[80:83], v[124:127], v[204:207], v[80:83]
	v_mfma_f32_16x16x32_bf16 v[76:79], v[140:143], v[204:207], v[76:79]
	v_mfma_f32_16x16x32_bf16 v[132:135], v[136:139], v[184:187], v[132:135]
	v_mfma_f32_16x16x32_bf16 v[128:131], v[144:147], v[184:187], v[128:131]
	v_mfma_f32_16x16x32_bf16 v[112:115], v[136:139], v[192:195], v[112:115]
	v_mfma_f32_16x16x32_bf16 v[108:111], v[144:147], v[192:195], v[108:111]
	v_mfma_f32_16x16x32_bf16 v[96:99], v[136:139], v[200:203], v[96:99]
	v_mfma_f32_16x16x32_bf16 v[92:95], v[144:147], v[200:203], v[92:95]
	v_mfma_f32_16x16x32_bf16 v[80:83], v[136:139], v[208:211], v[80:83]
	v_mfma_f32_16x16x32_bf16 v[76:79], v[144:147], v[208:211], v[76:79]
	s_setprio 0
	s_setprio 1
	v_mfma_f32_16x16x32_bf16 v[120:123], v[148:151], v[174:177], v[120:123]
	v_mfma_f32_16x16x32_bf16 v[116:119], v[156:159], v[174:177], v[116:119]
	v_mfma_f32_16x16x32_bf16 v[104:107], v[148:151], v[188:191], v[104:107]
	v_mfma_f32_16x16x32_bf16 v[100:103], v[156:159], v[188:191], v[100:103]
	v_mfma_f32_16x16x32_bf16 v[88:91], v[148:151], v[196:199], v[88:91]
	v_mfma_f32_16x16x32_bf16 v[84:87], v[156:159], v[196:199], v[84:87]
	v_mfma_f32_16x16x32_bf16 v[72:75], v[148:151], v[204:207], v[72:75]
	v_mfma_f32_16x16x32_bf16 v[68:71], v[156:159], v[204:207], v[68:71]
	v_mfma_f32_16x16x32_bf16 v[120:123], v[152:155], v[184:187], v[120:123]
	v_mfma_f32_16x16x32_bf16 v[116:119], v[170:173], v[184:187], v[116:119]
	v_mfma_f32_16x16x32_bf16 v[104:107], v[152:155], v[192:195], v[104:107]
	v_mfma_f32_16x16x32_bf16 v[100:103], v[170:173], v[192:195], v[100:103]
	v_mfma_f32_16x16x32_bf16 v[88:91], v[152:155], v[200:203], v[88:91]
	v_mfma_f32_16x16x32_bf16 v[84:87], v[170:173], v[200:203], v[84:87]
	v_mfma_f32_16x16x32_bf16 v[72:75], v[152:155], v[208:211], v[72:75]
	v_mfma_f32_16x16x32_bf16 v[68:71], v[170:173], v[208:211], v[68:71]
	s_barrier
; #define PG8_STAGE(bufoff, gbase, voff) do { _Pragma("unroll") for (int _i = 0; _i < 2; ++_i) \
;         __builtin_amdgcn_global_load_lds((const unsigned*)((const char*)(gbase) + (voff)[_i]), (PG8_LAS unsigned*)(lds + (bufoff) + ldsw + _i * 8192), 16, 0, 0); } while (0)
; #define PG8_LDA(dst, b, h) do { _Pragma("unroll") for (int m = 0; m < 4; ++m) _Pragma("unroll") for (int k = 0; k < 2; ++k) dst[m][k] = *(const PG8_LAS bf16x8*)(lds + PG8_SA(b, h) + aoff + m * 2048 + k * 1024); } while (0)
; #define PG8_MMA(ai, bj, At, Bt) do { __builtin_amdgcn_s_setprio(1); _Pragma("unroll") for (int m = 0; m < 4; ++m) _Pragma("unroll") for (int n = 0; n < 2; ++n) _Pragma("unroll") for (int k = 0; k < 2; ++k) \
;         acc[ai][bj][m][n] = __builtin_amdgcn_mfma_f32_16x16x32_bf16(Bt[n][k], At[m][k], acc[ai][bj][m][n], 0, 0, 0); __builtin_amdgcn_s_setprio(0); } while (0)
; #define PG8_WAIT_V(n) asm volatile("s_waitcnt vmcnt(" #n ")" ::: "memory")
; #define PG8_WAIT_L(n) asm volatile("s_waitcnt lgkmcnt(" #n ")" ::: "memory")
; #define PG8_BAR __builtin_amdgcn_s_barrier()
; #define PG8_SCHED __builtin_amdgcn_sched_barrier(0)
; template <class Epi, class Sched, bool ALIGN_EPI = false, bool SP2 = false>
; __device__ __forceinline__ void gemm_phase(PG8_LAS unsigned char* lds, const Gemm g, const Sched& S, const Epi& E) {
;     ...
;             PG8_LDA(At, 1, 1); PG8_STAGE(PG8_SB(1, 0), b3, voffB); PG8_STAGE(PG8_SB(1, 1), b3 + hstep, voffB); PG8_STAGE(PG8_SA(1, 0), a3, voffA);
;             PG8_WAIT_V(8); PG8_WAIT_L(0); PG8_BAR; PG8_MMA(1, 0, At, B0); PG8_MMA(1, 1, At, B1); PG8_BAR; PG8_SCHED;
	s_add_i32 s26, s26, s50
	v_lshl_add_u64 v[178:179], v[178:179], 0, s[60:61]
	s_mov_b32 m0, s26
	ds_read_b128 v[174:177], v183 offset:49152
	ds_read_b128 v[184:187], v183 offset:50176
	ds_read_b128 v[188:191], v183 offset:51200
	ds_read_b128 v[192:195], v183 offset:52224
	ds_read_b128 v[196:199], v183 offset:53248
	ds_read_b128 v[200:203], v183 offset:54272
	ds_read_b128 v[204:207], v183 offset:55296
	ds_read_b128 v[208:211], v183 offset:56320
	global_load_lds_dwordx4 v[178:179], off
	s_add_i32 m0, s26, 0x2000
	s_add_u32 s44, s44, 0x200080
	v_lshl_add_u64 v[178:179], v[212:213], 0, s[60:61]
	s_addc_u32 s45, s45, 0
	s_add_i32 s26, s31, s50
	global_load_lds_dwordx4 v[178:179], off
	v_lshl_add_u64 v[178:179], s[44:45], 0, v[2:3]
	s_mov_b32 m0, s26
	s_nop 0
	global_load_lds_dwordx4 v[178:179], off
	v_lshl_add_u64 v[178:179], s[44:45], 0, v[160:161]
	s_add_i32 m0, s26, 0x2000
	s_nop 0
	global_load_lds_dwordx4 v[178:179], off
	v_lshl_add_u64 v[178:179], v[214:215], 0, s[60:61]
	s_mov_b32 m0, s56
	s_nop 0
	global_load_lds_dwordx4 v[178:179], off
	v_lshl_add_u64 v[178:179], v[216:217], 0, s[60:61]
	s_mov_b32 m0, s57
	s_nop 0
	global_load_lds_dwordx4 v[178:179], off
	s_setprio 0
	s_waitcnt vmcnt(8)
	s_waitcnt lgkmcnt(0)
	s_setprio 1
	s_barrier
	v_mfma_f32_16x16x32_bf16 v[64:67], v[124:127], v[174:177], v[64:67]
	v_mfma_f32_16x16x32_bf16 v[60:63], v[140:143], v[174:177], v[60:63]
	v_mfma_f32_16x16x32_bf16 v[48:51], v[124:127], v[188:191], v[48:51]
	v_mfma_f32_16x16x32_bf16 v[44:47], v[140:143], v[188:191], v[44:47]
	v_mfma_f32_16x16x32_bf16 v[32:35], v[124:127], v[196:199], v[32:35]
	v_mfma_f32_16x16x32_bf16 v[28:31], v[140:143], v[196:199], v[28:31]
	v_mfma_f32_16x16x32_bf16 v[16:19], v[124:127], v[204:207], v[16:19]
	v_mfma_f32_16x16x32_bf16 v[12:15], v[140:143], v[204:207], v[12:15]
	v_mfma_f32_16x16x32_bf16 v[64:67], v[136:139], v[184:187], v[64:67]
	v_mfma_f32_16x16x32_bf16 v[60:63], v[144:147], v[184:187], v[60:63]
	v_mfma_f32_16x16x32_bf16 v[48:51], v[136:139], v[192:195], v[48:51]
	v_mfma_f32_16x16x32_bf16 v[44:47], v[144:147], v[192:195], v[44:47]
	v_mfma_f32_16x16x32_bf16 v[32:35], v[136:139], v[200:203], v[32:35]
	v_mfma_f32_16x16x32_bf16 v[28:31], v[144:147], v[200:203], v[28:31]
	v_mfma_f32_16x16x32_bf16 v[16:19], v[136:139], v[208:211], v[16:19]
	v_mfma_f32_16x16x32_bf16 v[12:15], v[144:147], v[208:211], v[12:15]
	s_setprio 0
	s_setprio 1
	v_mfma_f32_16x16x32_bf16 v[56:59], v[148:151], v[174:177], v[56:59]
	v_mfma_f32_16x16x32_bf16 v[52:55], v[156:159], v[174:177], v[52:55]
	v_mfma_f32_16x16x32_bf16 v[40:43], v[148:151], v[188:191], v[40:43]
	v_mfma_f32_16x16x32_bf16 v[36:39], v[156:159], v[188:191], v[36:39]
	v_mfma_f32_16x16x32_bf16 v[24:27], v[148:151], v[196:199], v[24:27]
	v_mfma_f32_16x16x32_bf16 v[20:23], v[156:159], v[196:199], v[20:23]
	v_mfma_f32_16x16x32_bf16 v[8:11], v[148:151], v[204:207], v[8:11]
	v_mfma_f32_16x16x32_bf16 v[4:7], v[156:159], v[204:207], v[4:7]
	v_mfma_f32_16x16x32_bf16 v[56:59], v[152:155], v[184:187], v[56:59]
	v_mfma_f32_16x16x32_bf16 v[52:55], v[170:173], v[184:187], v[52:55]
	v_mfma_f32_16x16x32_bf16 v[40:43], v[152:155], v[192:195], v[40:43]
	v_mfma_f32_16x16x32_bf16 v[36:39], v[170:173], v[192:195], v[36:39]
	v_mfma_f32_16x16x32_bf16 v[24:27], v[152:155], v[200:203], v[24:27]
	v_mfma_f32_16x16x32_bf16 v[20:23], v[170:173], v[200:203], v[20:23]
	v_mfma_f32_16x16x32_bf16 v[8:11], v[152:155], v[208:211], v[8:11]
	v_mfma_f32_16x16x32_bf16 v[4:7], v[170:173], v[208:211], v[4:7]
	s_barrier
	s_add_i32 s74, s74, 2
	s_add_u32 s6, s6, 0x100
	s_addc_u32 s7, s7, 0
	s_add_u32 s66, s66, 0x100
	s_addc_u32 s70, s70, 0
	s_cmpk_gt_u32 s74, 0x7d
	s_cbranch_scc0 .LBB0_2176
	s_and_b64 vcc, exec, s[18:19]
	s_cbranch_vccz .LBB0_2179
	s_barrier
